# adds batched global loads in multi-scale pooling (was ~45 serialized round trips per run) and Q-rope table prefetch one tile ahead in attention
# speedup vs baseline: 1.0183x; 1.0183x over previous
.LBB0_565:
	s_and_b32 s60, s45, 1
	s_bfe_u32 s59, s45, 0x60001
	s_ashr_i32 s0, s45, 7
	s_lshl_b32 s1, s60, 2
	s_lshl_b32 s50, s59, 7
	s_add_i32 s16, s1, s20
	s_ashr_i32 s1, s0, 31
	s_add_i32 s51, s50, 0xffffff80
	s_lshl_b64 s[18:19], s[0:1], 13
	v_or_b32_e32 v0, s50, v112
	v_add_u32_e32 v6, s51, v119
	v_or_b32_e32 v0, s18, v0
	v_mov_b64_e32 v[4:5], s[56:57]
	v_cmp_gt_u32_e32 vcc, s37, v6
	v_mad_u64_u32 v[0:1], s[66:67], v0, s53, v[4:5]
	s_lshl_b32 s18, s16, 6
	s_lshl_b32 s17, s0, 13
	v_cndmask_b32_e32 v28, 0, v6, vcc
	v_mad_i32_i24 v1, s19, v207, v1
	s_ashr_i32 s19, s18, 31
	v_add_u32_e32 v6, s17, v28
	v_lshl_add_u64 v[0:1], s[18:19], 1, v[0:1]
	v_lshlrev_b32_e32 v152, 1, v84
	v_mad_i64_i32 v[4:5], s[18:19], v6, s53, v[4:5]
	s_lshl_b32 s8, s60, 7
	v_lshl_add_u64 v[106:107], v[0:1], 0, v[152:153]
	v_lshl_add_u64 v[4:5], v[4:5], 0, s[8:9]
	v_lshlrev_b32_e32 v152, 1, v86
	v_lshl_add_u64 v[4:5], v[4:5], 0, v[152:153]
	global_load_dwordx4 v[0:3], v[106:107], off
	global_load_dwordx4 v[8:11], v[106:107], off offset:64
	v_add_u32_e32 v12, s51, v119
	v_cmp_gt_u32_e32 vcc, s37, v12
	s_nop 1
	v_cndmask_b32_e32 v29, 0, v12, vcc
	v_add_u32_e32 v12, s17, v29
	v_mov_b64_e32 v[14:15], s[56:57]
	v_mad_i64_i32 v[14:15], s[18:19], v12, s53, v[14:15]
	v_lshl_add_u64 v[14:15], v[14:15], 0, s[8:9]
	v_lshl_add_u64 v[14:15], v[14:15], 0, v[152:153]
	global_load_dwordx4 v[44:47], v[14:15], off offset:1024
	v_add_u32_e32 v12, s51, v120
	v_cmp_gt_u32_e32 vcc, s37, v12
	s_nop 1
	v_cndmask_b32_e32 v29, 0, v12, vcc
	v_add_u32_e32 v12, s17, v29
	v_mov_b64_e32 v[14:15], s[56:57]
	v_mad_i64_i32 v[14:15], s[18:19], v12, s53, v[14:15]
	v_lshl_add_u64 v[14:15], v[14:15], 0, s[8:9]
	v_lshl_add_u64 v[14:15], v[14:15], 0, v[152:153]
	global_load_dwordx4 v[48:51], v[14:15], off offset:1024
	v_add_u32_e32 v12, s51, v121
	v_cmp_gt_u32_e32 vcc, s37, v12
	s_nop 1
	v_cndmask_b32_e32 v29, 0, v12, vcc
	v_add_u32_e32 v12, s17, v29
	v_mov_b64_e32 v[14:15], s[56:57]
	v_mad_i64_i32 v[14:15], s[18:19], v12, s53, v[14:15]
	v_lshl_add_u64 v[14:15], v[14:15], 0, s[8:9]
	v_lshl_add_u64 v[14:15], v[14:15], 0, v[152:153]
	global_load_dwordx4 v[52:55], v[14:15], off offset:1024
	v_add_u32_e32 v12, s51, v122
	v_cmp_gt_u32_e32 vcc, s37, v12
	s_nop 1
	v_cndmask_b32_e32 v29, 0, v12, vcc
	v_add_u32_e32 v12, s17, v29
	v_mov_b64_e32 v[14:15], s[56:57]
	v_mad_i64_i32 v[14:15], s[18:19], v12, s53, v[14:15]
	v_lshl_add_u64 v[14:15], v[14:15], 0, s[8:9]
	v_lshl_add_u64 v[14:15], v[14:15], 0, v[152:153]
	global_load_dwordx4 v[56:59], v[14:15], off offset:1024
	v_add_u32_e32 v12, s51, v123
	v_cmp_gt_u32_e32 vcc, s37, v12
	s_nop 1
	v_cndmask_b32_e32 v29, 0, v12, vcc
	v_add_u32_e32 v12, s17, v29
	v_mov_b64_e32 v[14:15], s[56:57]
	v_mad_i64_i32 v[14:15], s[18:19], v12, s53, v[14:15]
	v_lshl_add_u64 v[14:15], v[14:15], 0, s[8:9]
	v_lshl_add_u64 v[14:15], v[14:15], 0, v[152:153]
	global_load_dwordx4 v[60:63], v[14:15], off offset:1024
	v_add_u32_e32 v12, s51, v124
	v_cmp_gt_u32_e32 vcc, s37, v12
	s_nop 1
	v_cndmask_b32_e32 v29, 0, v12, vcc
	v_add_u32_e32 v12, s17, v29
	v_mov_b64_e32 v[14:15], s[56:57]
	v_mad_i64_i32 v[14:15], s[18:19], v12, s53, v[14:15]
	v_lshl_add_u64 v[14:15], v[14:15], 0, s[8:9]
	v_lshl_add_u64 v[14:15], v[14:15], 0, v[152:153]
	global_load_dwordx4 v[64:67], v[14:15], off offset:1024
	s_and_saveexec_b64 s[18:19], s[46:47]
	v_add_u32_e32 v12, s51, v119
	v_cmp_gt_u32_e32 vcc, s37, v12
	s_nop 1
	v_cndmask_b32_e32 v29, 0, v12, vcc
	v_lshlrev_b32_e32 v12, 4, v29
	v_ashrrev_i32_e32 v13, 31, v12
	v_lshl_add_u64 v[16:17], v[12:13], 2, s[12:13]
	global_load_dwordx4 v[68:71], v[16:17], off
	global_load_dwordx4 v[72:75], v[16:17], off offset:16
	global_load_dwordx4 v[76:79], v[16:17], off offset:32
	global_load_dwordx4 v[80:83], v[16:17], off offset:48
	v_add_u32_e32 v12, s51, v120
	v_cmp_gt_u32_e32 vcc, s37, v12
	s_nop 1
	v_cndmask_b32_e32 v29, 0, v12, vcc
	v_lshlrev_b32_e32 v12, 4, v29
	v_ashrrev_i32_e32 v13, 31, v12
	v_lshl_add_u64 v[16:17], v[12:13], 2, s[12:13]
	global_load_dwordx4 v[176:179], v[16:17], off
	global_load_dwordx4 v[180:183], v[16:17], off offset:16
	global_load_dwordx4 v[184:187], v[16:17], off offset:32
	global_load_dwordx4 v[188:191], v[16:17], off offset:48
	v_add_u32_e32 v12, s51, v121
	v_cmp_gt_u32_e32 vcc, s37, v12
	s_nop 1
	v_cndmask_b32_e32 v29, 0, v12, vcc
	v_lshlrev_b32_e32 v12, 4, v29
	v_ashrrev_i32_e32 v13, 31, v12
	v_lshl_add_u64 v[16:17], v[12:13], 2, s[12:13]
	global_load_dwordx4 v[192:195], v[16:17], off
	global_load_dwordx4 v[196:199], v[16:17], off offset:16
	global_load_dwordx4 v[144:147], v[16:17], off offset:32
	global_load_dwordx4 v[148:151], v[16:17], off offset:48
	v_add_u32_e32 v12, s51, v122
	v_cmp_gt_u32_e32 vcc, s37, v12
	s_nop 1
	v_cndmask_b32_e32 v29, 0, v12, vcc
	v_lshlrev_b32_e32 v12, 4, v29
	v_ashrrev_i32_e32 v13, 31, v12
	v_lshl_add_u64 v[16:17], v[12:13], 2, s[12:13]
	global_load_dwordx4 v[210:213], v[16:17], off
	global_load_dwordx4 v[214:217], v[16:17], off offset:16
	global_load_dwordx4 v[218:221], v[16:17], off offset:32
	global_load_dwordx4 v[224:227], v[16:17], off offset:48
	v_add_u32_e32 v12, s51, v123
	v_cmp_gt_u32_e32 vcc, s37, v12
	s_nop 1
	v_cndmask_b32_e32 v29, 0, v12, vcc
	v_lshlrev_b32_e32 v12, 4, v29
	v_ashrrev_i32_e32 v13, 31, v12
	v_lshl_add_u64 v[16:17], v[12:13], 2, s[12:13]
	global_load_dwordx4 v[228:231], v[16:17], off
	global_load_dwordx4 v[232:235], v[16:17], off offset:16
	global_load_dwordx4 v[236:239], v[16:17], off offset:32
	global_load_dwordx4 v[172:175], v[16:17], off offset:48
	s_or_b64 exec, exec, s[18:19]
	s_barrier
	s_waitcnt vmcnt(16)
	v_add_u32_e32 v12, s51, v119
	v_cmp_gt_u32_e32 vcc, s37, v12
	s_nop 1
	v_cndmask_b32_e32 v7, 0, v47, vcc
	v_cndmask_b32_e32 v6, 0, v46, vcc
	v_cndmask_b32_e32 v5, 0, v45, vcc
	v_cndmask_b32_e32 v4, 0, v44, vcc
	v_lshlrev_b32_e32 v13, 16, v5
	v_lshlrev_b32_e32 v12, 16, v4
	v_and_b32_e32 v15, 0xffff0000, v5
	v_and_b32_e32 v14, 0xffff0000, v4
	v_and_b32_e32 v17, 0xffff0000, v6
	v_lshlrev_b32_e32 v16, 16, v6
	v_and_b32_e32 v19, 0xffff0000, v7
	v_lshlrev_b32_e32 v18, 16, v7
	ds_bpermute_b32 v26, v113, v12
	ds_bpermute_b32 v24, v113, v14
	ds_bpermute_b32 v27, v113, v13
	ds_bpermute_b32 v25, v113, v15
	ds_bpermute_b32 v22, v113, v16
	ds_bpermute_b32 v23, v113, v17
	ds_bpermute_b32 v20, v113, v18
	ds_bpermute_b32 v21, v113, v19
	s_and_saveexec_b64 s[18:19], s[46:47]
	s_waitcnt lgkmcnt(4)
	v_pk_mul_f32 v[24:25], v[88:89], v[24:25]
	s_waitcnt lgkmcnt(2)
	v_pk_mul_f32 v[22:23], v[88:89], v[22:23]
	s_waitcnt lgkmcnt(0)
	v_pk_mul_f32 v[20:21], v[88:89], v[20:21]
	v_pk_mul_f32 v[26:27], v[88:89], v[26:27]
	v_mov_b32_e32 v40, v68
	v_mov_b32_e32 v41, v70
	v_mov_b32_e32 v42, v76
	v_mov_b32_e32 v43, v78
	v_mov_b32_e32 v30, v77
	v_mov_b32_e32 v31, v79
	v_mov_b32_e32 v6, v69
	v_mov_b32_e32 v7, v71
	v_pk_mul_f32 v[4:5], v[22:23], v[80:81]
	v_pk_mul_f32 v[20:21], v[20:21], v[82:83]
	v_pk_mul_f32 v[24:25], v[24:25], v[30:31]
	v_pk_mul_f32 v[22:23], v[26:27], v[42:43]
	v_pk_fma_f32 v[4:5], v[72:73], v[16:17], v[4:5]
	v_pk_fma_f32 v[16:17], v[74:75], v[18:19], v[20:21]
	v_pk_fma_f32 v[6:7], v[6:7], v[14:15], v[24:25]
	v_pk_fma_f32 v[12:13], v[40:41], v[12:13], v[22:23]
	v_and_b32_sdwa v15, v4, v203 dst_sel:DWORD dst_unused:UNUSED_PAD src0_sel:WORD_1 src1_sel:DWORD
	v_and_b32_sdwa v19, v16, v203 dst_sel:DWORD dst_unused:UNUSED_PAD src0_sel:WORD_1 src1_sel:DWORD
	v_and_b32_sdwa v22, v7, v203 dst_sel:DWORD dst_unused:UNUSED_PAD src0_sel:WORD_1 src1_sel:DWORD
	v_and_b32_sdwa v23, v6, v203 dst_sel:DWORD dst_unused:UNUSED_PAD src0_sel:WORD_1 src1_sel:DWORD
	v_and_b32_sdwa v14, v5, v203 dst_sel:DWORD dst_unused:UNUSED_PAD src0_sel:WORD_1 src1_sel:DWORD
	v_and_b32_sdwa v18, v17, v203 dst_sel:DWORD dst_unused:UNUSED_PAD src0_sel:WORD_1 src1_sel:DWORD
	v_and_b32_sdwa v20, v13, v203 dst_sel:DWORD dst_unused:UNUSED_PAD src0_sel:WORD_1 src1_sel:DWORD
	v_and_b32_sdwa v21, v12, v203 dst_sel:DWORD dst_unused:UNUSED_PAD src0_sel:WORD_1 src1_sel:DWORD
	v_add3_u32 v4, v4, v15, s54
	v_add3_u32 v15, v16, v19, s54
	v_add3_u32 v7, v7, v22, s54
	v_add3_u32 v6, v6, v23, s54
	v_add3_u32 v5, v5, v14, s54
	v_add3_u32 v14, v17, v18, s54
	v_add3_u32 v12, v12, v21, s54
	v_add3_u32 v13, v13, v20, s54
	v_lshrrev_b32_e32 v4, 16, v4
	v_lshrrev_b32_e32 v15, 16, v15
	v_and_b32_e32 v7, 0xffff0000, v7
	v_and_b32_e32 v16, 0xffff0000, v6
	v_and_or_b32 v6, v5, s52, v4
	v_or_b32_sdwa v5, v7, v13 dst_sel:DWORD dst_unused:UNUSED_PAD src0_sel:DWORD src1_sel:WORD_1
	v_or_b32_sdwa v4, v16, v12 dst_sel:DWORD dst_unused:UNUSED_PAD src0_sel:DWORD src1_sel:WORD_1
	v_and_or_b32 v7, v14, s52, v15
	s_or_b64 exec, exec, s[18:19]
	ds_write_b128 v85, v[4:7]
	s_and_saveexec_b64 s[18:19], s[46:47]
	v_add_u32_e32 v12, s51, v124
	v_cmp_gt_u32_e32 vcc, s37, v12
	s_nop 1
	v_cndmask_b32_e32 v29, 0, v12, vcc
	v_lshlrev_b32_e32 v12, 4, v29
	v_ashrrev_i32_e32 v13, 31, v12
	v_lshl_add_u64 v[16:17], v[12:13], 2, s[12:13]
	global_load_dwordx4 v[68:71], v[16:17], off
	global_load_dwordx4 v[72:75], v[16:17], off offset:16
	global_load_dwordx4 v[76:79], v[16:17], off offset:32
	global_load_dwordx4 v[80:83], v[16:17], off offset:48
	s_or_b64 exec, exec, s[18:19]
	s_waitcnt vmcnt(16)
	v_add_u32_e32 v12, s51, v120
	v_cmp_gt_u32_e32 vcc, s37, v12
	s_nop 1
	v_cndmask_b32_e32 v7, 0, v51, vcc
	v_cndmask_b32_e32 v6, 0, v50, vcc
	v_cndmask_b32_e32 v5, 0, v49, vcc
	v_cndmask_b32_e32 v4, 0, v48, vcc
	v_lshlrev_b32_e32 v13, 16, v5
	v_lshlrev_b32_e32 v12, 16, v4
	v_and_b32_e32 v15, 0xffff0000, v5
	v_and_b32_e32 v14, 0xffff0000, v4
	v_and_b32_e32 v17, 0xffff0000, v6
	v_lshlrev_b32_e32 v16, 16, v6
	v_and_b32_e32 v19, 0xffff0000, v7
	v_lshlrev_b32_e32 v18, 16, v7
	ds_bpermute_b32 v26, v113, v12
	ds_bpermute_b32 v24, v113, v14
	ds_bpermute_b32 v27, v113, v13
	ds_bpermute_b32 v25, v113, v15
	ds_bpermute_b32 v22, v113, v16
	ds_bpermute_b32 v23, v113, v17
	ds_bpermute_b32 v20, v113, v18
	ds_bpermute_b32 v21, v113, v19
	s_and_saveexec_b64 s[18:19], s[46:47]
	s_waitcnt lgkmcnt(4)
	v_pk_mul_f32 v[24:25], v[88:89], v[24:25]
	s_waitcnt lgkmcnt(2)
	v_pk_mul_f32 v[22:23], v[88:89], v[22:23]
	s_waitcnt lgkmcnt(0)
	v_pk_mul_f32 v[20:21], v[88:89], v[20:21]
	v_pk_mul_f32 v[26:27], v[88:89], v[26:27]
	v_mov_b32_e32 v40, v176
	v_mov_b32_e32 v41, v178
	v_mov_b32_e32 v42, v184
	v_mov_b32_e32 v43, v186
	v_mov_b32_e32 v30, v185
	v_mov_b32_e32 v31, v187
	v_mov_b32_e32 v6, v177
	v_mov_b32_e32 v7, v179
	v_pk_mul_f32 v[4:5], v[22:23], v[188:189]
	v_pk_mul_f32 v[20:21], v[20:21], v[190:191]
	v_pk_mul_f32 v[24:25], v[24:25], v[30:31]
	v_pk_mul_f32 v[22:23], v[26:27], v[42:43]
	v_pk_fma_f32 v[4:5], v[180:181], v[16:17], v[4:5]
	v_pk_fma_f32 v[16:17], v[182:183], v[18:19], v[20:21]
	v_pk_fma_f32 v[6:7], v[6:7], v[14:15], v[24:25]
	v_pk_fma_f32 v[12:13], v[40:41], v[12:13], v[22:23]
	v_and_b32_sdwa v15, v4, v203 dst_sel:DWORD dst_unused:UNUSED_PAD src0_sel:WORD_1 src1_sel:DWORD
	v_and_b32_sdwa v19, v16, v203 dst_sel:DWORD dst_unused:UNUSED_PAD src0_sel:WORD_1 src1_sel:DWORD
	v_and_b32_sdwa v22, v7, v203 dst_sel:DWORD dst_unused:UNUSED_PAD src0_sel:WORD_1 src1_sel:DWORD
	v_and_b32_sdwa v23, v6, v203 dst_sel:DWORD dst_unused:UNUSED_PAD src0_sel:WORD_1 src1_sel:DWORD
	v_and_b32_sdwa v14, v5, v203 dst_sel:DWORD dst_unused:UNUSED_PAD src0_sel:WORD_1 src1_sel:DWORD
	v_and_b32_sdwa v18, v17, v203 dst_sel:DWORD dst_unused:UNUSED_PAD src0_sel:WORD_1 src1_sel:DWORD
	v_and_b32_sdwa v20, v13, v203 dst_sel:DWORD dst_unused:UNUSED_PAD src0_sel:WORD_1 src1_sel:DWORD
	v_and_b32_sdwa v21, v12, v203 dst_sel:DWORD dst_unused:UNUSED_PAD src0_sel:WORD_1 src1_sel:DWORD
	v_add3_u32 v4, v4, v15, s54
	v_add3_u32 v15, v16, v19, s54
	v_add3_u32 v7, v7, v22, s54
	v_add3_u32 v6, v6, v23, s54
	v_add3_u32 v5, v5, v14, s54
	v_add3_u32 v14, v17, v18, s54
	v_add3_u32 v12, v12, v21, s54
	v_add3_u32 v13, v13, v20, s54
	v_lshrrev_b32_e32 v4, 16, v4
	v_lshrrev_b32_e32 v15, 16, v15
	v_and_b32_e32 v7, 0xffff0000, v7
	v_and_b32_e32 v16, 0xffff0000, v6
	v_and_or_b32 v6, v5, s52, v4
	v_or_b32_sdwa v5, v7, v13 dst_sel:DWORD dst_unused:UNUSED_PAD src0_sel:DWORD src1_sel:WORD_1
	v_or_b32_sdwa v4, v16, v12 dst_sel:DWORD dst_unused:UNUSED_PAD src0_sel:DWORD src1_sel:WORD_1
	v_and_or_b32 v7, v14, s52, v15
	s_or_b64 exec, exec, s[18:19]
	ds_write_b128 v138, v[4:7]
	v_add_u32_e32 v12, s51, v125
	v_cmp_gt_u32_e32 vcc, s37, v12
	s_nop 1
	v_cndmask_b32_e32 v29, 0, v12, vcc
	v_add_u32_e32 v12, s17, v29
	v_mov_b64_e32 v[14:15], s[56:57]
	v_mad_i64_i32 v[14:15], s[18:19], v12, s53, v[14:15]
	v_lshl_add_u64 v[14:15], v[14:15], 0, s[8:9]
	v_lshl_add_u64 v[14:15], v[92:93], 1, v[14:15]
	global_load_dwordx4 v[44:47], v[14:15], off offset:1280
	v_add_u32_e32 v12, s51, v127
	v_cmp_gt_u32_e32 vcc, s37, v12
	s_nop 1
	v_cndmask_b32_e32 v29, 0, v12, vcc
	v_add_u32_e32 v12, s17, v29
	v_mov_b64_e32 v[14:15], s[56:57]
	v_mad_i64_i32 v[14:15], s[18:19], v12, s53, v[14:15]
	v_lshl_add_u64 v[14:15], v[14:15], 0, s[8:9]
	v_lshl_add_u64 v[14:15], v[94:95], 1, v[14:15]
	global_load_dwordx4 v[48:51], v[14:15], off offset:1280
	v_add_u32_e32 v12, s51, v129
	v_cmp_gt_u32_e32 vcc, s37, v12
	s_nop 1
	v_cndmask_b32_e32 v29, 0, v12, vcc
	v_add_u32_e32 v12, s17, v29
	v_mov_b64_e32 v[14:15], s[56:57]
	v_mad_i64_i32 v[14:15], s[18:19], v12, s53, v[14:15]
	v_lshl_add_u64 v[14:15], v[14:15], 0, s[8:9]
	v_lshl_add_u64 v[14:15], v[96:97], 1, v[14:15]
	global_load_dwordx4 v[176:179], v[14:15], off offset:1280
	v_add_u32_e32 v12, s51, v131
	v_cmp_gt_u32_e32 vcc, s37, v12
	s_nop 1
	v_cndmask_b32_e32 v29, 0, v12, vcc
	v_add_u32_e32 v12, s17, v29
	v_mov_b64_e32 v[14:15], s[56:57]
	v_mad_i64_i32 v[14:15], s[18:19], v12, s53, v[14:15]
	v_lshl_add_u64 v[14:15], v[14:15], 0, s[8:9]
	v_lshl_add_u64 v[14:15], v[98:99], 1, v[14:15]
	global_load_dwordx4 v[180:183], v[14:15], off offset:1280
	v_add_u32_e32 v12, s51, v133
	v_cmp_gt_u32_e32 vcc, s37, v12
	s_nop 1
	v_cndmask_b32_e32 v29, 0, v12, vcc
	v_add_u32_e32 v12, s17, v29
	v_mov_b64_e32 v[14:15], s[56:57]
	v_mad_i64_i32 v[14:15], s[18:19], v12, s53, v[14:15]
	v_lshl_add_u64 v[14:15], v[14:15], 0, s[8:9]
	v_lshl_add_u64 v[14:15], v[100:101], 1, v[14:15]
	global_load_dwordx4 v[184:187], v[14:15], off offset:1280
	v_add_u32_e32 v12, s51, v135
	v_cmp_gt_u32_e32 vcc, s37, v12
	s_nop 1
	v_cndmask_b32_e32 v29, 0, v12, vcc
	v_add_u32_e32 v12, s17, v29
	v_mov_b64_e32 v[14:15], s[56:57]
	v_mad_i64_i32 v[14:15], s[18:19], v12, s53, v[14:15]
	v_lshl_add_u64 v[14:15], v[14:15], 0, s[8:9]
	v_lshl_add_u64 v[14:15], v[102:103], 1, v[14:15]
	global_load_dwordx4 v[188:191], v[14:15], off offset:1280
	s_waitcnt vmcnt(18)
	v_add_u32_e32 v12, s51, v121
	v_cmp_gt_u32_e32 vcc, s37, v12
	s_nop 1
	v_cndmask_b32_e32 v7, 0, v55, vcc
	v_cndmask_b32_e32 v6, 0, v54, vcc
	v_cndmask_b32_e32 v5, 0, v53, vcc
	v_cndmask_b32_e32 v4, 0, v52, vcc
	v_lshlrev_b32_e32 v13, 16, v5
	v_lshlrev_b32_e32 v12, 16, v4
	v_and_b32_e32 v15, 0xffff0000, v5
	v_and_b32_e32 v14, 0xffff0000, v4
	v_and_b32_e32 v17, 0xffff0000, v6
	v_lshlrev_b32_e32 v16, 16, v6
	v_and_b32_e32 v19, 0xffff0000, v7
	v_lshlrev_b32_e32 v18, 16, v7
	ds_bpermute_b32 v26, v113, v12
	ds_bpermute_b32 v24, v113, v14
	ds_bpermute_b32 v27, v113, v13
	ds_bpermute_b32 v25, v113, v15
	ds_bpermute_b32 v22, v113, v16
	ds_bpermute_b32 v23, v113, v17
	ds_bpermute_b32 v20, v113, v18
	ds_bpermute_b32 v21, v113, v19
	s_and_saveexec_b64 s[18:19], s[46:47]
	s_waitcnt lgkmcnt(4)
	v_pk_mul_f32 v[24:25], v[88:89], v[24:25]
	s_waitcnt lgkmcnt(2)
	v_pk_mul_f32 v[22:23], v[88:89], v[22:23]
	s_waitcnt lgkmcnt(0)
	v_pk_mul_f32 v[20:21], v[88:89], v[20:21]
	v_pk_mul_f32 v[26:27], v[88:89], v[26:27]
	v_mov_b32_e32 v40, v192
	v_mov_b32_e32 v41, v194
	v_mov_b32_e32 v42, v144
	v_mov_b32_e32 v43, v146
	v_mov_b32_e32 v30, v145
	v_mov_b32_e32 v31, v147
	v_mov_b32_e32 v6, v193
	v_mov_b32_e32 v7, v195
	v_pk_mul_f32 v[4:5], v[22:23], v[148:149]
	v_pk_mul_f32 v[20:21], v[20:21], v[150:151]
	v_pk_mul_f32 v[24:25], v[24:25], v[30:31]
	v_pk_mul_f32 v[22:23], v[26:27], v[42:43]
	v_pk_fma_f32 v[4:5], v[196:197], v[16:17], v[4:5]
	v_pk_fma_f32 v[16:17], v[198:199], v[18:19], v[20:21]
	v_pk_fma_f32 v[6:7], v[6:7], v[14:15], v[24:25]
	v_pk_fma_f32 v[12:13], v[40:41], v[12:13], v[22:23]
	v_and_b32_sdwa v15, v4, v203 dst_sel:DWORD dst_unused:UNUSED_PAD src0_sel:WORD_1 src1_sel:DWORD
	v_and_b32_sdwa v19, v16, v203 dst_sel:DWORD dst_unused:UNUSED_PAD src0_sel:WORD_1 src1_sel:DWORD
	v_and_b32_sdwa v22, v7, v203 dst_sel:DWORD dst_unused:UNUSED_PAD src0_sel:WORD_1 src1_sel:DWORD
	v_and_b32_sdwa v23, v6, v203 dst_sel:DWORD dst_unused:UNUSED_PAD src0_sel:WORD_1 src1_sel:DWORD
	v_and_b32_sdwa v14, v5, v203 dst_sel:DWORD dst_unused:UNUSED_PAD src0_sel:WORD_1 src1_sel:DWORD
	v_and_b32_sdwa v18, v17, v203 dst_sel:DWORD dst_unused:UNUSED_PAD src0_sel:WORD_1 src1_sel:DWORD
	v_and_b32_sdwa v20, v13, v203 dst_sel:DWORD dst_unused:UNUSED_PAD src0_sel:WORD_1 src1_sel:DWORD
	v_and_b32_sdwa v21, v12, v203 dst_sel:DWORD dst_unused:UNUSED_PAD src0_sel:WORD_1 src1_sel:DWORD
	v_add3_u32 v4, v4, v15, s54
	v_add3_u32 v15, v16, v19, s54
	v_add3_u32 v7, v7, v22, s54
	v_add3_u32 v6, v6, v23, s54
	v_add3_u32 v5, v5, v14, s54
	v_add3_u32 v14, v17, v18, s54
	v_add3_u32 v12, v12, v21, s54
	v_add3_u32 v13, v13, v20, s54
	v_lshrrev_b32_e32 v4, 16, v4
	v_lshrrev_b32_e32 v15, 16, v15
	v_and_b32_e32 v7, 0xffff0000, v7
	v_and_b32_e32 v16, 0xffff0000, v6
	v_and_or_b32 v6, v5, s52, v4
	v_or_b32_sdwa v5, v7, v13 dst_sel:DWORD dst_unused:UNUSED_PAD src0_sel:DWORD src1_sel:WORD_1
	v_or_b32_sdwa v4, v16, v12 dst_sel:DWORD dst_unused:UNUSED_PAD src0_sel:DWORD src1_sel:WORD_1
	v_and_or_b32 v7, v14, s52, v15
	s_or_b64 exec, exec, s[18:19]
	ds_write_b128 v139, v[4:7]
	s_waitcnt vmcnt(14)
	v_add_u32_e32 v12, s51, v122
	v_cmp_gt_u32_e32 vcc, s37, v12
	s_nop 1
	v_cndmask_b32_e32 v7, 0, v59, vcc
	v_cndmask_b32_e32 v6, 0, v58, vcc
	v_cndmask_b32_e32 v5, 0, v57, vcc
	v_cndmask_b32_e32 v4, 0, v56, vcc
	v_lshlrev_b32_e32 v13, 16, v5
	v_lshlrev_b32_e32 v12, 16, v4
	v_and_b32_e32 v15, 0xffff0000, v5
	v_and_b32_e32 v14, 0xffff0000, v4
	v_and_b32_e32 v17, 0xffff0000, v6
	v_lshlrev_b32_e32 v16, 16, v6
	v_and_b32_e32 v19, 0xffff0000, v7
	v_lshlrev_b32_e32 v18, 16, v7
	ds_bpermute_b32 v26, v113, v12
	ds_bpermute_b32 v24, v113, v14
	ds_bpermute_b32 v27, v113, v13
	ds_bpermute_b32 v25, v113, v15
	ds_bpermute_b32 v22, v113, v16
	ds_bpermute_b32 v23, v113, v17
	ds_bpermute_b32 v20, v113, v18
	ds_bpermute_b32 v21, v113, v19
	s_and_saveexec_b64 s[18:19], s[46:47]
	s_waitcnt lgkmcnt(4)
	v_pk_mul_f32 v[24:25], v[88:89], v[24:25]
	s_waitcnt lgkmcnt(2)
	v_pk_mul_f32 v[22:23], v[88:89], v[22:23]
	s_waitcnt lgkmcnt(0)
	v_pk_mul_f32 v[20:21], v[88:89], v[20:21]
	v_pk_mul_f32 v[26:27], v[88:89], v[26:27]
	v_mov_b32_e32 v40, v210
	v_mov_b32_e32 v41, v212
	v_mov_b32_e32 v42, v218
	v_mov_b32_e32 v43, v220
	v_mov_b32_e32 v30, v219
	v_mov_b32_e32 v31, v221
	v_mov_b32_e32 v6, v211
	v_mov_b32_e32 v7, v213
	v_pk_mul_f32 v[4:5], v[22:23], v[224:225]
	v_pk_mul_f32 v[20:21], v[20:21], v[226:227]
	v_pk_mul_f32 v[24:25], v[24:25], v[30:31]
	v_pk_mul_f32 v[22:23], v[26:27], v[42:43]
	v_pk_fma_f32 v[4:5], v[214:215], v[16:17], v[4:5]
	v_pk_fma_f32 v[16:17], v[216:217], v[18:19], v[20:21]
	v_pk_fma_f32 v[6:7], v[6:7], v[14:15], v[24:25]
	v_pk_fma_f32 v[12:13], v[40:41], v[12:13], v[22:23]
	v_and_b32_sdwa v15, v4, v203 dst_sel:DWORD dst_unused:UNUSED_PAD src0_sel:WORD_1 src1_sel:DWORD
	v_and_b32_sdwa v19, v16, v203 dst_sel:DWORD dst_unused:UNUSED_PAD src0_sel:WORD_1 src1_sel:DWORD
	v_and_b32_sdwa v22, v7, v203 dst_sel:DWORD dst_unused:UNUSED_PAD src0_sel:WORD_1 src1_sel:DWORD
	v_and_b32_sdwa v23, v6, v203 dst_sel:DWORD dst_unused:UNUSED_PAD src0_sel:WORD_1 src1_sel:DWORD
	v_and_b32_sdwa v14, v5, v203 dst_sel:DWORD dst_unused:UNUSED_PAD src0_sel:WORD_1 src1_sel:DWORD
	v_and_b32_sdwa v18, v17, v203 dst_sel:DWORD dst_unused:UNUSED_PAD src0_sel:WORD_1 src1_sel:DWORD
	v_and_b32_sdwa v20, v13, v203 dst_sel:DWORD dst_unused:UNUSED_PAD src0_sel:WORD_1 src1_sel:DWORD
	v_and_b32_sdwa v21, v12, v203 dst_sel:DWORD dst_unused:UNUSED_PAD src0_sel:WORD_1 src1_sel:DWORD
	v_add3_u32 v4, v4, v15, s54
	v_add3_u32 v15, v16, v19, s54
	v_add3_u32 v7, v7, v22, s54
	v_add3_u32 v6, v6, v23, s54
	v_add3_u32 v5, v5, v14, s54
	v_add3_u32 v14, v17, v18, s54
	v_add3_u32 v12, v12, v21, s54
	v_add3_u32 v13, v13, v20, s54
	v_lshrrev_b32_e32 v4, 16, v4
	v_lshrrev_b32_e32 v15, 16, v15
	v_and_b32_e32 v7, 0xffff0000, v7
	v_and_b32_e32 v16, 0xffff0000, v6
	v_and_or_b32 v6, v5, s52, v4
	v_or_b32_sdwa v5, v7, v13 dst_sel:DWORD dst_unused:UNUSED_PAD src0_sel:DWORD src1_sel:WORD_1
	v_or_b32_sdwa v4, v16, v12 dst_sel:DWORD dst_unused:UNUSED_PAD src0_sel:DWORD src1_sel:WORD_1
	v_and_or_b32 v7, v14, s52, v15
	s_or_b64 exec, exec, s[18:19]
	ds_write_b128 v140, v[4:7]
	s_waitcnt vmcnt(10)
	v_add_u32_e32 v12, s51, v123
	v_cmp_gt_u32_e32 vcc, s37, v12
	s_nop 1
	v_cndmask_b32_e32 v7, 0, v63, vcc
	v_cndmask_b32_e32 v6, 0, v62, vcc
	v_cndmask_b32_e32 v5, 0, v61, vcc
	v_cndmask_b32_e32 v4, 0, v60, vcc
	v_lshlrev_b32_e32 v13, 16, v5
	v_lshlrev_b32_e32 v12, 16, v4
	v_and_b32_e32 v15, 0xffff0000, v5
	v_and_b32_e32 v14, 0xffff0000, v4
	v_and_b32_e32 v17, 0xffff0000, v6
	v_lshlrev_b32_e32 v16, 16, v6
	v_and_b32_e32 v19, 0xffff0000, v7
	v_lshlrev_b32_e32 v18, 16, v7
	ds_bpermute_b32 v26, v113, v12
	ds_bpermute_b32 v24, v113, v14
	ds_bpermute_b32 v27, v113, v13
	ds_bpermute_b32 v25, v113, v15
	ds_bpermute_b32 v22, v113, v16
	ds_bpermute_b32 v23, v113, v17
	ds_bpermute_b32 v20, v113, v18
	ds_bpermute_b32 v21, v113, v19
	s_and_saveexec_b64 s[18:19], s[46:47]
	s_waitcnt lgkmcnt(4)
	v_pk_mul_f32 v[24:25], v[88:89], v[24:25]
	s_waitcnt lgkmcnt(2)
	v_pk_mul_f32 v[22:23], v[88:89], v[22:23]
	s_waitcnt lgkmcnt(0)
	v_pk_mul_f32 v[20:21], v[88:89], v[20:21]
	v_pk_mul_f32 v[26:27], v[88:89], v[26:27]
	v_mov_b32_e32 v40, v228
	v_mov_b32_e32 v41, v230
	v_mov_b32_e32 v42, v236
	v_mov_b32_e32 v43, v238
	v_mov_b32_e32 v30, v237
	v_mov_b32_e32 v31, v239
	v_mov_b32_e32 v6, v229
	v_mov_b32_e32 v7, v231
	v_pk_mul_f32 v[4:5], v[22:23], v[172:173]
	v_pk_mul_f32 v[20:21], v[20:21], v[174:175]
	v_pk_mul_f32 v[24:25], v[24:25], v[30:31]
	v_pk_mul_f32 v[22:23], v[26:27], v[42:43]
	v_pk_fma_f32 v[4:5], v[232:233], v[16:17], v[4:5]
	v_pk_fma_f32 v[16:17], v[234:235], v[18:19], v[20:21]
	v_pk_fma_f32 v[6:7], v[6:7], v[14:15], v[24:25]
	v_pk_fma_f32 v[12:13], v[40:41], v[12:13], v[22:23]
	v_and_b32_sdwa v15, v4, v203 dst_sel:DWORD dst_unused:UNUSED_PAD src0_sel:WORD_1 src1_sel:DWORD
	v_and_b32_sdwa v19, v16, v203 dst_sel:DWORD dst_unused:UNUSED_PAD src0_sel:WORD_1 src1_sel:DWORD
	v_and_b32_sdwa v22, v7, v203 dst_sel:DWORD dst_unused:UNUSED_PAD src0_sel:WORD_1 src1_sel:DWORD
	v_and_b32_sdwa v23, v6, v203 dst_sel:DWORD dst_unused:UNUSED_PAD src0_sel:WORD_1 src1_sel:DWORD
	v_and_b32_sdwa v14, v5, v203 dst_sel:DWORD dst_unused:UNUSED_PAD src0_sel:WORD_1 src1_sel:DWORD
	v_and_b32_sdwa v18, v17, v203 dst_sel:DWORD dst_unused:UNUSED_PAD src0_sel:WORD_1 src1_sel:DWORD
	v_and_b32_sdwa v20, v13, v203 dst_sel:DWORD dst_unused:UNUSED_PAD src0_sel:WORD_1 src1_sel:DWORD
	v_and_b32_sdwa v21, v12, v203 dst_sel:DWORD dst_unused:UNUSED_PAD src0_sel:WORD_1 src1_sel:DWORD
	v_add3_u32 v4, v4, v15, s54
	v_add3_u32 v15, v16, v19, s54
	v_add3_u32 v7, v7, v22, s54
	v_add3_u32 v6, v6, v23, s54
	v_add3_u32 v5, v5, v14, s54
	v_add3_u32 v14, v17, v18, s54
	v_add3_u32 v12, v12, v21, s54
	v_add3_u32 v13, v13, v20, s54
	v_lshrrev_b32_e32 v4, 16, v4
	v_lshrrev_b32_e32 v15, 16, v15
	v_and_b32_e32 v7, 0xffff0000, v7
	v_and_b32_e32 v16, 0xffff0000, v6
	v_and_or_b32 v6, v5, s52, v4
	v_or_b32_sdwa v5, v7, v13 dst_sel:DWORD dst_unused:UNUSED_PAD src0_sel:DWORD src1_sel:WORD_1
	v_or_b32_sdwa v4, v16, v12 dst_sel:DWORD dst_unused:UNUSED_PAD src0_sel:DWORD src1_sel:WORD_1
	v_and_or_b32 v7, v14, s52, v15
	s_or_b64 exec, exec, s[18:19]
	ds_write_b128 v141, v[4:7]
	s_waitcnt vmcnt(6)
	v_add_u32_e32 v12, s51, v124
	v_cmp_gt_u32_e32 vcc, s37, v12
	s_nop 1
	v_cndmask_b32_e32 v7, 0, v67, vcc
	v_cndmask_b32_e32 v6, 0, v66, vcc
	v_cndmask_b32_e32 v5, 0, v65, vcc
	v_cndmask_b32_e32 v4, 0, v64, vcc
	v_lshlrev_b32_e32 v13, 16, v5
	v_lshlrev_b32_e32 v12, 16, v4
	v_and_b32_e32 v15, 0xffff0000, v5
	v_and_b32_e32 v14, 0xffff0000, v4
	v_and_b32_e32 v17, 0xffff0000, v6
	v_lshlrev_b32_e32 v16, 16, v6
	v_and_b32_e32 v19, 0xffff0000, v7
	v_lshlrev_b32_e32 v18, 16, v7
	ds_bpermute_b32 v26, v113, v12
	ds_bpermute_b32 v24, v113, v14
	ds_bpermute_b32 v27, v113, v13
	ds_bpermute_b32 v25, v113, v15
	ds_bpermute_b32 v22, v113, v16
	ds_bpermute_b32 v23, v113, v17
	ds_bpermute_b32 v20, v113, v18
	ds_bpermute_b32 v21, v113, v19
	s_and_saveexec_b64 s[18:19], s[46:47]
	s_waitcnt lgkmcnt(4)
	v_pk_mul_f32 v[24:25], v[88:89], v[24:25]
	s_waitcnt lgkmcnt(2)
	v_pk_mul_f32 v[22:23], v[88:89], v[22:23]
	s_waitcnt lgkmcnt(0)
	v_pk_mul_f32 v[20:21], v[88:89], v[20:21]
	v_pk_mul_f32 v[26:27], v[88:89], v[26:27]
	v_mov_b32_e32 v40, v68
	v_mov_b32_e32 v41, v70
	v_mov_b32_e32 v42, v76
	v_mov_b32_e32 v43, v78
	v_mov_b32_e32 v30, v77
	v_mov_b32_e32 v31, v79
	v_mov_b32_e32 v6, v69
	v_mov_b32_e32 v7, v71
	v_pk_mul_f32 v[4:5], v[22:23], v[80:81]
	v_pk_mul_f32 v[20:21], v[20:21], v[82:83]
	v_pk_mul_f32 v[24:25], v[24:25], v[30:31]
	v_pk_mul_f32 v[22:23], v[26:27], v[42:43]
	v_pk_fma_f32 v[4:5], v[72:73], v[16:17], v[4:5]
	v_pk_fma_f32 v[16:17], v[74:75], v[18:19], v[20:21]
	v_pk_fma_f32 v[6:7], v[6:7], v[14:15], v[24:25]
	v_pk_fma_f32 v[12:13], v[40:41], v[12:13], v[22:23]
	v_and_b32_sdwa v15, v4, v203 dst_sel:DWORD dst_unused:UNUSED_PAD src0_sel:WORD_1 src1_sel:DWORD
	v_and_b32_sdwa v19, v16, v203 dst_sel:DWORD dst_unused:UNUSED_PAD src0_sel:WORD_1 src1_sel:DWORD
	v_and_b32_sdwa v22, v7, v203 dst_sel:DWORD dst_unused:UNUSED_PAD src0_sel:WORD_1 src1_sel:DWORD
	v_and_b32_sdwa v23, v6, v203 dst_sel:DWORD dst_unused:UNUSED_PAD src0_sel:WORD_1 src1_sel:DWORD
	v_and_b32_sdwa v14, v5, v203 dst_sel:DWORD dst_unused:UNUSED_PAD src0_sel:WORD_1 src1_sel:DWORD
	v_and_b32_sdwa v18, v17, v203 dst_sel:DWORD dst_unused:UNUSED_PAD src0_sel:WORD_1 src1_sel:DWORD
	v_and_b32_sdwa v20, v13, v203 dst_sel:DWORD dst_unused:UNUSED_PAD src0_sel:WORD_1 src1_sel:DWORD
	v_and_b32_sdwa v21, v12, v203 dst_sel:DWORD dst_unused:UNUSED_PAD src0_sel:WORD_1 src1_sel:DWORD
	v_add3_u32 v4, v4, v15, s54
	v_add3_u32 v15, v16, v19, s54
	v_add3_u32 v7, v7, v22, s54
	v_add3_u32 v6, v6, v23, s54
	v_add3_u32 v5, v5, v14, s54
	v_add3_u32 v14, v17, v18, s54
	v_add3_u32 v12, v12, v21, s54
	v_add3_u32 v13, v13, v20, s54
	v_lshrrev_b32_e32 v4, 16, v4
	v_lshrrev_b32_e32 v15, 16, v15
	v_and_b32_e32 v7, 0xffff0000, v7
	v_and_b32_e32 v16, 0xffff0000, v6
	v_and_or_b32 v6, v5, s52, v4
	v_or_b32_sdwa v5, v7, v13 dst_sel:DWORD dst_unused:UNUSED_PAD src0_sel:DWORD src1_sel:WORD_1
	v_or_b32_sdwa v4, v16, v12 dst_sel:DWORD dst_unused:UNUSED_PAD src0_sel:DWORD src1_sel:WORD_1
	v_and_or_b32 v7, v14, s52, v15
	s_or_b64 exec, exec, s[18:19]
	ds_write_b128 v142, v[4:7]
	s_waitcnt vmcnt(5)
	v_add_u32_e32 v12, s51, v125
	v_cmp_gt_u32_e32 vcc, s37, v12
	s_nop 1
	v_cndmask_b32_e32 v4, 0, v44, vcc
	v_cndmask_b32_e32 v5, 0, v45, vcc
	v_cndmask_b32_e32 v6, 0, v46, vcc
	v_cndmask_b32_e32 v7, 0, v47, vcc
	ds_write_b16 v126, v4 offset:55296
	ds_write_b16_d16_hi v126, v4 offset:56080
	ds_write_b16 v126, v5 offset:56864
	ds_write_b16_d16_hi v126, v5 offset:57648
	ds_write_b16 v126, v6 offset:58432
	ds_write_b16_d16_hi v126, v6 offset:59216
	ds_write_b16 v126, v7 offset:60000
	ds_write_b16_d16_hi v126, v7 offset:60784
	s_waitcnt vmcnt(4)
	v_add_u32_e32 v12, s51, v127
	v_cmp_gt_u32_e32 vcc, s37, v12
	s_nop 1
	v_cndmask_b32_e32 v4, 0, v48, vcc
	v_cndmask_b32_e32 v5, 0, v49, vcc
	v_cndmask_b32_e32 v6, 0, v50, vcc
	v_cndmask_b32_e32 v7, 0, v51, vcc
	ds_write_b16 v128, v4 offset:56320
	ds_write_b16_d16_hi v128, v4 offset:57104
	ds_write_b16 v128, v5 offset:57888
	ds_write_b16_d16_hi v128, v5 offset:58672
	ds_write_b16 v128, v6 offset:59456
	ds_write_b16_d16_hi v128, v6 offset:60240
	ds_write_b16 v128, v7 offset:61024
	ds_write_b16_d16_hi v128, v7 offset:61808
	s_waitcnt vmcnt(3)
	v_add_u32_e32 v12, s51, v129
	v_cmp_gt_u32_e32 vcc, s37, v12
	s_nop 1
	v_cndmask_b32_e32 v4, 0, v176, vcc
	v_cndmask_b32_e32 v5, 0, v177, vcc
	v_cndmask_b32_e32 v6, 0, v178, vcc
	v_cndmask_b32_e32 v7, 0, v179, vcc
	ds_write_b16 v130, v4 offset:57344
	ds_write_b16_d16_hi v130, v4 offset:58128
	ds_write_b16 v130, v5 offset:58912
	ds_write_b16_d16_hi v130, v5 offset:59696
	ds_write_b16 v130, v6 offset:60480
	ds_write_b16_d16_hi v130, v6 offset:61264
	ds_write_b16 v130, v7 offset:62048
	ds_write_b16_d16_hi v130, v7 offset:62832
	s_waitcnt vmcnt(2)
	v_add_u32_e32 v12, s51, v131
	v_cmp_gt_u32_e32 vcc, s37, v12
	s_nop 1
	v_cndmask_b32_e32 v4, 0, v180, vcc
	v_cndmask_b32_e32 v5, 0, v181, vcc
	v_cndmask_b32_e32 v6, 0, v182, vcc
	v_cndmask_b32_e32 v7, 0, v183, vcc
	ds_write_b16 v132, v4 offset:58368
	ds_write_b16_d16_hi v132, v4 offset:59152
	ds_write_b16 v132, v5 offset:59936
	ds_write_b16_d16_hi v132, v5 offset:60720
	ds_write_b16 v132, v6 offset:61504
	ds_write_b16_d16_hi v132, v6 offset:62288
	ds_write_b16 v132, v7 offset:63072
	ds_write_b16_d16_hi v132, v7 offset:63856
	s_waitcnt vmcnt(1)
	v_add_u32_e32 v12, s51, v133
	v_cmp_gt_u32_e32 vcc, s37, v12
	s_nop 1
	v_cndmask_b32_e32 v4, 0, v184, vcc
	v_cndmask_b32_e32 v5, 0, v185, vcc
	v_cndmask_b32_e32 v6, 0, v186, vcc
	v_cndmask_b32_e32 v7, 0, v187, vcc
	ds_write_b16 v134, v4 offset:59392
	ds_write_b16_d16_hi v134, v4 offset:60176
	ds_write_b16 v134, v5 offset:60960
	ds_write_b16_d16_hi v134, v5 offset:61744
	ds_write_b16 v134, v6 offset:62528
	ds_write_b16_d16_hi v134, v6 offset:63312
	ds_write_b16 v134, v7 offset:64096
	ds_write_b16_d16_hi v134, v7 offset:64880
	s_waitcnt vmcnt(0)
	v_add_u32_e32 v12, s51, v135
	v_cmp_gt_u32_e32 vcc, s37, v12
	s_nop 1
	v_cndmask_b32_e32 v4, 0, v188, vcc
	v_cndmask_b32_e32 v5, 0, v189, vcc
	v_cndmask_b32_e32 v6, 0, v190, vcc
	v_cndmask_b32_e32 v7, 0, v191, vcc
	ds_write_b16 v136, v4 offset:60416
	ds_write_b16_d16_hi v136, v4 offset:61200
	ds_write_b16 v136, v5 offset:61984
	ds_write_b16_d16_hi v136, v5 offset:62768
	ds_write_b16 v136, v6 offset:63552
	ds_write_b16_d16_hi v136, v6 offset:64336
	ds_write_b16 v136, v7 offset:65120
	ds_write_b16_d16_hi v137, v7 offset:5488
	s_lshr_b32 s18, s45, 1
	s_and_b32 s18, s18, 63
	v_lshl_or_b32 v12, s18, 7, v112
	v_lshlrev_b32_e32 v152, 6, v12
	v_lshl_add_u64 v[108:109], s[12:13], 0, v[152:153]
	v_lshlrev_b32_e32 v152, 10, v12
	v_cndmask_b32_e64 v12, 0, 1, s[10:11]
	s_nop 1
	v_readfirstlane_b32 s18, v12
	s_nop 1
	s_lshl_b32 s18, s18, 8
	s_add_i32 s18, s44, s18
	s_ashr_i32 s19, s18, 31
	s_lshl_b64 s[18:19], s[18:19], 1
	s_ashr_i32 s17, s16, 31
	s_lshl_b64 s[16:17], s[16:17], 2
	v_readlane_b32 s8, v254, 0
	s_nop 1
	s_add_u32 s16, s8, s16
	v_readlane_b32 s8, v254, 1
	s_nop 1
	s_addc_u32 s17, s8, s17
	s_sub_i32 s60, 0x80, s50
	s_sub_i32 s61, 0x2080, s50
	s_lshl_b64 s[0:1], s[0:1], 23
	s_add_u32 s0, s18, s0
	s_addc_u32 s1, s19, s1
	s_mov_b32 s18, 0xd000
	s_mov_b32 s19, s21
	s_waitcnt lgkmcnt(0)
	s_barrier
	s_and_saveexec_b64 s[50:51], s[48:49]
	global_load_dwordx4 v[176:179], v[108:109], off
	global_load_dwordx4 v[180:183], v[108:109], off offset:32
	global_load_dwordx4 v[184:187], v[108:109], off offset:48
	global_load_dwordx4 v[188:191], v[108:109], off offset:16
	s_or_b64 exec, exec, s[50:51]
	global_load_dword v4, v153, s[16:17]
	s_mov_b64 s[16:17], 0
	s_waitcnt vmcnt(0)
	v_mul_f32_e32 v143, 0x3fb8aa3b, v4
	v_lshl_add_u64 v[4:5], s[0:1], 0, v[152:153]
	v_lshl_add_u64 v[110:111], v[104:105], 0, v[4:5]
	s_branch .LBB0_579

.LBB0_579:
	s_cmpk_lg_u32 s16, 0xc000
	s_cselect_b32 s8, s18, 0x27000
	v_mov_b64_e32 v[82:83], v[2:3]
	v_lshl_add_u64 v[4:5], s[8:9], 1, v[106:107]
	v_mov_b64_e32 v[80:81], v[0:1]
	global_load_dwordx4 v[0:3], v[4:5], off
	s_nop 0
	global_load_dwordx4 v[4:7], v[4:5], off offset:64
	v_lshlrev_b32_e32 v13, 16, v81
	v_lshlrev_b32_e32 v12, 16, v80
	v_and_b32_e32 v15, 0xffff0000, v81
	v_and_b32_e32 v14, 0xffff0000, v80
	v_and_b32_e32 v17, 0xffff0000, v82
	v_lshlrev_b32_e32 v16, 16, v82
	v_and_b32_e32 v19, 0xffff0000, v83
	v_lshlrev_b32_e32 v18, 16, v83
	ds_bpermute_b32 v26, v114, v12
	ds_bpermute_b32 v24, v114, v14
	ds_bpermute_b32 v27, v114, v13
	ds_bpermute_b32 v25, v114, v15
	ds_bpermute_b32 v22, v114, v16
	ds_bpermute_b32 v23, v114, v17
	ds_bpermute_b32 v20, v114, v18
	ds_bpermute_b32 v21, v114, v19
	s_and_saveexec_b64 s[0:1], s[48:49]
	s_cbranch_execz .LBB0_581
	v_mov_b32_e32 v28, v176
	v_mov_b32_e32 v29, v177
	v_mov_b32_e32 v30, v178
	v_mov_b32_e32 v31, v179
	v_mov_b32_e32 v32, v180
	v_mov_b32_e32 v33, v181
	v_mov_b32_e32 v34, v182
	v_mov_b32_e32 v35, v183
	v_mov_b32_e32 v36, v184
	v_mov_b32_e32 v37, v185
	v_mov_b32_e32 v38, v186
	v_mov_b32_e32 v39, v187
	v_mov_b32_e32 v40, v188
	v_mov_b32_e32 v41, v189
	v_mov_b32_e32 v42, v190
	v_mov_b32_e32 v43, v191
	global_load_dwordx4 v[176:179], v[108:109], off offset:1024
	global_load_dwordx4 v[180:183], v[108:109], off offset:1056
	global_load_dwordx4 v[184:187], v[108:109], off offset:1072
	global_load_dwordx4 v[188:191], v[108:109], off offset:1040
	s_waitcnt lgkmcnt(4)
	v_pk_mul_f32 v[24:25], v[90:91], v[24:25]
	s_waitcnt lgkmcnt(2)
	v_pk_mul_f32 v[22:23], v[90:91], v[22:23]
	s_waitcnt lgkmcnt(0)
	v_pk_mul_f32 v[20:21], v[90:91], v[20:21]
	v_pk_mul_f32 v[26:27], v[90:91], v[26:27]
	v_mov_b32_e32 v45, v30
	v_mov_b32_e32 v47, v34
	v_mov_b32_e32 v34, v33
	v_mov_b32_e32 v46, v32
	v_mov_b32_e32 v30, v29
	v_pk_mul_f32 v[22:23], v[22:23], v[36:37]
	v_pk_mul_f32 v[20:21], v[20:21], v[38:39]
	v_pk_mul_f32 v[24:25], v[24:25], v[34:35]
	v_mov_b32_e32 v44, v28
	v_pk_mul_f32 v[26:27], v[26:27], v[46:47]
	v_pk_fma_f32 v[16:17], v[40:41], v[16:17], v[22:23]
	v_pk_fma_f32 v[18:19], v[42:43], v[18:19], v[20:21]
	v_pk_fma_f32 v[14:15], v[30:31], v[14:15], v[24:25]
	v_pk_fma_f32 v[12:13], v[44:45], v[12:13], v[26:27]
	v_and_b32_sdwa v21, v16, v203 dst_sel:DWORD dst_unused:UNUSED_PAD src0_sel:WORD_1 src1_sel:DWORD
	v_and_b32_sdwa v23, v18, v203 dst_sel:DWORD dst_unused:UNUSED_PAD src0_sel:WORD_1 src1_sel:DWORD
	v_and_b32_sdwa v26, v15, v203 dst_sel:DWORD dst_unused:UNUSED_PAD src0_sel:WORD_1 src1_sel:DWORD
	v_and_b32_sdwa v27, v14, v203 dst_sel:DWORD dst_unused:UNUSED_PAD src0_sel:WORD_1 src1_sel:DWORD
	v_and_b32_sdwa v20, v17, v203 dst_sel:DWORD dst_unused:UNUSED_PAD src0_sel:WORD_1 src1_sel:DWORD
	v_and_b32_sdwa v22, v19, v203 dst_sel:DWORD dst_unused:UNUSED_PAD src0_sel:WORD_1 src1_sel:DWORD
	v_and_b32_sdwa v24, v13, v203 dst_sel:DWORD dst_unused:UNUSED_PAD src0_sel:WORD_1 src1_sel:DWORD
	v_and_b32_sdwa v25, v12, v203 dst_sel:DWORD dst_unused:UNUSED_PAD src0_sel:WORD_1 src1_sel:DWORD
	v_add3_u32 v16, v16, v21, s54
	v_add3_u32 v18, v18, v23, s54
	v_add3_u32 v15, v15, v26, s54
	v_add3_u32 v14, v14, v27, s54
	v_add3_u32 v17, v17, v20, s54
	v_add3_u32 v19, v19, v22, s54
	v_add3_u32 v12, v12, v25, s54
	v_add3_u32 v13, v13, v24, s54
	v_lshrrev_b32_e32 v16, 16, v16
	v_lshrrev_b32_e32 v18, 16, v18
	v_and_b32_e32 v15, 0xffff0000, v15
	v_and_b32_e32 v14, 0xffff0000, v14
	v_and_or_b32 v82, v17, s52, v16
	v_or_b32_sdwa v81, v15, v13 dst_sel:DWORD dst_unused:UNUSED_PAD src0_sel:DWORD src1_sel:WORD_1
	v_or_b32_sdwa v80, v14, v12 dst_sel:DWORD dst_unused:UNUSED_PAD src0_sel:DWORD src1_sel:WORD_1
	v_and_or_b32 v83, v19, s52, v18

.LBB0_612:
	s_ashr_i32 s1, s0, 31
	s_lshl_b64 s[10:11], s[0:1], 10
	s_add_u32 s10, s34, s10
	s_addc_u32 s11, s35, s11
	s_bfe_u32 s16, s0, 0x90004
	s_and_b32 s17, s0, 0xffffe000
	s_lshl_b32 s1, s16, 4
	s_mul_i32 s16, s16, 0x1a000
	s_mul_hi_i32 s18, s17, 0x1a00
	s_mulk_i32 s17, 0x1a00
	s_add_u32 s16, s16, s17
	s_addc_u32 s17, 0, s18
	s_add_u32 s16, s34, s16
	s_addc_u32 s17, s35, s17
	s_lshl_b32 s18, s8, 4
	s_and_b32 s20, s18, 0x1ff0
	v_sub_u32_e32 v0, s20, v200
	s_and_b32 s21, s18, 0xffffe000
	v_mad_i64_i32 v[144:145], vcc, s21, v207, v[170:171]
	v_mov_b32_e32 v141, s20
	v_mov_b32_e32 v143, 0
	v_add_u32_e32 v140, 0, v0
	v_cmp_gt_u32_e32 vcc, s37, v140
	s_nop 1
	v_cndmask_b32_e32 v140, v141, v140, vcc
	v_mul_i32_i24_e32 v142, 0xd00, v140
	v_lshl_add_u64 v[146:147], v[142:143], 1, v[144:145]
	global_load_dwordx4 v[76:79], v[146:147], off offset:1536
	v_add_u32_e32 v140, 1, v0
	v_cmp_gt_u32_e32 vcc, s37, v140
	s_nop 1
	v_cndmask_b32_e32 v140, v141, v140, vcc
	v_mul_i32_i24_e32 v142, 0xd00, v140
	v_lshl_add_u64 v[146:147], v[142:143], 1, v[144:145]
	global_load_dwordx4 v[80:83], v[146:147], off offset:1536
	v_add_u32_e32 v140, 2, v0
	v_cmp_gt_u32_e32 vcc, s37, v140
	s_and_b64 vcc, s[38:39], vcc
	s_nop 1
	v_cndmask_b32_e32 v140, v141, v140, vcc
	v_mul_i32_i24_e32 v142, 0xd00, v140
	v_lshl_add_u64 v[146:147], v[142:143], 1, v[144:145]
	global_load_dwordx4 v[84:87], v[146:147], off offset:1536
	v_add_u32_e32 v140, 3, v0
	v_cmp_gt_u32_e32 vcc, s37, v140
	s_and_b64 vcc, s[38:39], vcc
	s_nop 1
	v_cndmask_b32_e32 v140, v141, v140, vcc
	v_mul_i32_i24_e32 v142, 0xd00, v140
	v_lshl_add_u64 v[146:147], v[142:143], 1, v[144:145]
	global_load_dwordx4 v[88:91], v[146:147], off offset:1536
	v_add_u32_e32 v140, 4, v0
	v_cmp_gt_u32_e32 vcc, s37, v140
	s_and_b64 vcc, s[40:41], vcc
	s_nop 1
	v_cndmask_b32_e32 v140, v141, v140, vcc
	v_mul_i32_i24_e32 v142, 0xd00, v140
	v_lshl_add_u64 v[146:147], v[142:143], 1, v[144:145]
	global_load_dwordx4 v[92:95], v[146:147], off offset:1536
	v_add_u32_e32 v140, 5, v0
	v_cmp_gt_u32_e32 vcc, s37, v140
	s_and_b64 vcc, s[40:41], vcc
	s_nop 1
	v_cndmask_b32_e32 v140, v141, v140, vcc
	v_mul_i32_i24_e32 v142, 0xd00, v140
	v_lshl_add_u64 v[146:147], v[142:143], 1, v[144:145]
	global_load_dwordx4 v[96:99], v[146:147], off offset:1536
	v_add_u32_e32 v140, 6, v0
	v_cmp_gt_u32_e32 vcc, s37, v140
	s_and_b64 vcc, s[40:41], vcc
	s_nop 1
	v_cndmask_b32_e32 v140, v141, v140, vcc
	v_mul_i32_i24_e32 v142, 0xd00, v140
	v_lshl_add_u64 v[146:147], v[142:143], 1, v[144:145]
	global_load_dwordx4 v[100:103], v[146:147], off offset:1536
	v_add_u32_e32 v140, 7, v0
	v_cmp_gt_u32_e32 vcc, s37, v140
	s_and_b64 vcc, s[40:41], vcc
	s_nop 1
	v_cndmask_b32_e32 v140, v141, v140, vcc
	v_mul_i32_i24_e32 v142, 0xd00, v140
	v_lshl_add_u64 v[146:147], v[142:143], 1, v[144:145]
	global_load_dwordx4 v[104:107], v[146:147], off offset:1536
	v_add_u32_e32 v140, 8, v0
	v_cndmask_b32_e64 v140, v141, v140, s[42:43]
	v_mul_i32_i24_e32 v142, 0xd00, v140
	v_lshl_add_u64 v[146:147], v[142:143], 1, v[144:145]
	global_load_dwordx4 v[108:111], v[146:147], off offset:1536
	v_add_u32_e32 v140, 9, v0
	v_cndmask_b32_e64 v140, v141, v140, s[42:43]
	v_mul_i32_i24_e32 v142, 0xd00, v140
	v_lshl_add_u64 v[146:147], v[142:143], 1, v[144:145]
	global_load_dwordx4 v[112:115], v[146:147], off offset:1536
	v_add_u32_e32 v140, 10, v0
	v_cndmask_b32_e64 v140, v141, v140, s[42:43]
	v_mul_i32_i24_e32 v142, 0xd00, v140
	v_lshl_add_u64 v[146:147], v[142:143], 1, v[144:145]
	global_load_dwordx4 v[116:119], v[146:147], off offset:1536
	v_add_u32_e32 v140, 11, v0
	v_cndmask_b32_e64 v140, v141, v140, s[42:43]
	v_mul_i32_i24_e32 v142, 0xd00, v140
	v_lshl_add_u64 v[146:147], v[142:143], 1, v[144:145]
	global_load_dwordx4 v[120:123], v[146:147], off offset:1536
	v_add_u32_e32 v140, 12, v0
	v_cndmask_b32_e64 v140, v141, v140, s[42:43]
	v_mul_i32_i24_e32 v142, 0xd00, v140
	v_lshl_add_u64 v[146:147], v[142:143], 1, v[144:145]
	global_load_dwordx4 v[124:127], v[146:147], off offset:1536
	v_add_u32_e32 v140, 13, v0
	v_cndmask_b32_e64 v140, v141, v140, s[42:43]
	v_mul_i32_i24_e32 v142, 0xd00, v140
	v_lshl_add_u64 v[146:147], v[142:143], 1, v[144:145]
	global_load_dwordx4 v[128:131], v[146:147], off offset:1536
	v_add_u32_e32 v140, 14, v0
	v_cndmask_b32_e64 v140, v141, v140, s[42:43]
	v_mul_i32_i24_e32 v142, 0xd00, v140
	v_lshl_add_u64 v[146:147], v[142:143], 1, v[144:145]
	global_load_dwordx4 v[132:135], v[146:147], off offset:1536
	v_add_u32_e32 v140, 15, v0
	v_cndmask_b32_e64 v140, v141, v140, s[42:43]
	v_mul_i32_i24_e32 v142, 0xd00, v140
	v_lshl_add_u64 v[146:147], v[142:143], 1, v[144:145]
	global_load_dwordx4 v[136:139], v[146:147], off offset:1536
	s_waitcnt vmcnt(0)
	v_cmp_gt_u32_e32 vcc, s37, v0
	v_mov_b32_e32 v1, s20
	s_and_b32 s19, s18, 0xffffe000
	v_cndmask_b32_e32 v2, v1, v0, vcc
	v_mad_i64_i32 v[16:17], s[18:19], s19, v207, v[170:171]
	v_mul_i32_i24_e32 v152, 0xd00, v2
	v_lshl_add_u64 v[2:3], v[152:153], 1, v[16:17]
	v_mov_b32_e32 v2, v76
	v_mov_b32_e32 v3, v77
	v_mov_b32_e32 v4, v78
	v_mov_b32_e32 v5, v79
	v_or_b32_e32 v38, s1, v200
	v_add_u32_e32 v39, s1, v201
	s_mov_b32 s18, -4
	s_waitcnt vmcnt(0)
	v_cndmask_b32_e32 v8, 0, v2, vcc
	v_add_u32_e32 v2, 1, v0
	v_cndmask_b32_e32 v12, 0, v5, vcc
	v_cndmask_b32_e32 v6, 0, v4, vcc
	v_cndmask_b32_e32 v7, 0, v3, vcc
	v_cmp_gt_u32_e32 vcc, s37, v2
	s_nop 1
	v_cndmask_b32_e32 v2, v1, v2, vcc
	v_mul_i32_i24_e32 v152, 0xd00, v2
	v_lshl_add_u64 v[2:3], v[152:153], 1, v[16:17]
	v_mov_b32_e32 v2, v80
	v_mov_b32_e32 v3, v81
	v_mov_b32_e32 v4, v82
	v_mov_b32_e32 v5, v83
	s_waitcnt vmcnt(0)
	v_cndmask_b32_e32 v10, 0, v2, vcc
	v_add_u32_e32 v2, 2, v0
	v_cndmask_b32_e32 v13, 0, v5, vcc
	v_cndmask_b32_e32 v14, 0, v4, vcc
	v_cndmask_b32_e32 v9, 0, v3, vcc
	v_cmp_gt_u32_e32 vcc, s37, v2
	s_and_b64 vcc, s[38:39], vcc
	s_nop 0
	v_cndmask_b32_e32 v2, v1, v2, vcc
	v_mul_i32_i24_e32 v152, 0xd00, v2
	v_lshl_add_u64 v[2:3], v[152:153], 1, v[16:17]
	v_mov_b32_e32 v2, v84
	v_mov_b32_e32 v3, v85
	v_mov_b32_e32 v4, v86
	v_mov_b32_e32 v5, v87
	s_waitcnt vmcnt(0)
	v_cndmask_b32_e32 v11, 0, v2, vcc
	v_add_u32_e32 v2, 3, v0
	v_cndmask_b32_e32 v15, 0, v5, vcc
	v_cndmask_b32_e32 v18, 0, v4, vcc
	v_cndmask_b32_e32 v19, 0, v3, vcc
	v_cmp_gt_u32_e32 vcc, s37, v2
	s_and_b64 vcc, s[38:39], vcc
	s_nop 0
	v_cndmask_b32_e32 v2, v1, v2, vcc
	v_mul_i32_i24_e32 v152, 0xd00, v2
	v_lshl_add_u64 v[2:3], v[152:153], 1, v[16:17]
	v_mov_b32_e32 v2, v88
	v_mov_b32_e32 v3, v89
	v_mov_b32_e32 v4, v90
	v_mov_b32_e32 v5, v91
	s_waitcnt vmcnt(0)
	v_cndmask_b32_e32 v23, 0, v2, vcc
	v_add_u32_e32 v2, 4, v0
	v_cndmask_b32_e32 v20, 0, v5, vcc
	v_cndmask_b32_e32 v21, 0, v4, vcc
	v_cndmask_b32_e32 v22, 0, v3, vcc
	v_cmp_gt_u32_e32 vcc, s37, v2
	s_and_b64 vcc, s[40:41], vcc
	s_nop 0
	v_cndmask_b32_e32 v2, v1, v2, vcc
	v_mul_i32_i24_e32 v152, 0xd00, v2
	v_lshl_add_u64 v[2:3], v[152:153], 1, v[16:17]
	v_mov_b32_e32 v2, v92
	v_mov_b32_e32 v3, v93
	v_mov_b32_e32 v4, v94
	v_mov_b32_e32 v5, v95
	s_waitcnt vmcnt(0)
	v_cndmask_b32_e32 v26, 0, v3, vcc
	v_cndmask_b32_e32 v27, 0, v2, vcc
	v_lshlrev_b32_e32 v2, 16, v8
	v_and_b32_e32 v3, 0xffff0000, v8
	v_cndmask_b32_e32 v24, 0, v5, vcc
	v_cndmask_b32_e32 v25, 0, v4, vcc
	v_pk_add_f32 v[2:3], v[2:3], 0 op_sel_hi:[1,0]
	v_lshlrev_b32_e32 v4, 16, v10
	v_and_b32_e32 v5, 0xffff0000, v10
	v_pk_add_f32 v[2:3], v[2:3], v[4:5]
	v_lshlrev_b32_e32 v4, 16, v11
	v_and_b32_e32 v5, 0xffff0000, v11
	v_pk_add_f32 v[2:3], v[2:3], v[4:5]
	v_lshlrev_b32_e32 v4, 16, v23
	v_and_b32_e32 v5, 0xffff0000, v23
	v_pk_add_f32 v[2:3], v[2:3], v[4:5]
	v_lshlrev_b32_e32 v4, 16, v27
	v_and_b32_e32 v5, 0xffff0000, v27
	v_pk_add_f32 v[10:11], v[2:3], v[4:5]
	v_lshlrev_b32_e32 v2, 16, v7
	v_and_b32_e32 v3, 0xffff0000, v7
	v_pk_add_f32 v[2:3], v[2:3], 0 op_sel_hi:[1,0]
	v_lshlrev_b32_e32 v4, 16, v9
	v_and_b32_e32 v5, 0xffff0000, v9
	v_pk_add_f32 v[2:3], v[2:3], v[4:5]
	v_lshlrev_b32_e32 v4, 16, v19
	v_and_b32_e32 v5, 0xffff0000, v19
	v_pk_add_f32 v[2:3], v[2:3], v[4:5]
	v_lshlrev_b32_e32 v4, 16, v22
	v_and_b32_e32 v5, 0xffff0000, v22
	v_pk_add_f32 v[2:3], v[2:3], v[4:5]
	v_lshlrev_b32_e32 v4, 16, v26
	v_and_b32_e32 v5, 0xffff0000, v26
	v_pk_add_f32 v[8:9], v[2:3], v[4:5]
	v_lshlrev_b32_e32 v2, 16, v6
	v_and_b32_e32 v3, 0xffff0000, v6
	v_pk_add_f32 v[2:3], v[2:3], 0 op_sel_hi:[1,0]
	v_lshlrev_b32_e32 v4, 16, v14
	v_and_b32_e32 v5, 0xffff0000, v14
	v_pk_add_f32 v[2:3], v[2:3], v[4:5]
	v_lshlrev_b32_e32 v4, 16, v18
	v_and_b32_e32 v5, 0xffff0000, v18
	v_pk_add_f32 v[2:3], v[2:3], v[4:5]
	v_lshlrev_b32_e32 v4, 16, v21
	v_and_b32_e32 v5, 0xffff0000, v21
	v_pk_add_f32 v[2:3], v[2:3], v[4:5]
	v_lshlrev_b32_e32 v4, 16, v25
	v_and_b32_e32 v5, 0xffff0000, v25
	v_pk_add_f32 v[6:7], v[2:3], v[4:5]
	v_lshlrev_b32_e32 v2, 16, v12
	v_and_b32_e32 v3, 0xffff0000, v12
	v_pk_add_f32 v[2:3], v[2:3], 0 op_sel_hi:[1,0]
	v_lshlrev_b32_e32 v4, 16, v13
	v_and_b32_e32 v5, 0xffff0000, v13
	v_pk_add_f32 v[2:3], v[2:3], v[4:5]
	v_lshlrev_b32_e32 v4, 16, v15
	v_and_b32_e32 v5, 0xffff0000, v15
	v_pk_add_f32 v[2:3], v[2:3], v[4:5]
	v_lshlrev_b32_e32 v4, 16, v20
	v_and_b32_e32 v5, 0xffff0000, v20
	v_pk_add_f32 v[2:3], v[2:3], v[4:5]
	v_lshlrev_b32_e32 v4, 16, v24
	v_and_b32_e32 v5, 0xffff0000, v24
	v_pk_add_f32 v[4:5], v[2:3], v[4:5]
	v_add_u32_e32 v2, 5, v0
	v_cmp_gt_u32_e32 vcc, s37, v2
	s_and_b64 vcc, s[40:41], vcc
	s_nop 0
	v_cndmask_b32_e32 v2, v1, v2, vcc
	v_mul_i32_i24_e32 v152, 0xd00, v2
	v_lshl_add_u64 v[2:3], v[152:153], 1, v[16:17]
	v_mov_b32_e32 v12, v96
	v_mov_b32_e32 v13, v97
	v_mov_b32_e32 v14, v98
	v_mov_b32_e32 v15, v99
	s_waitcnt vmcnt(0)
	v_cndmask_b32_e32 v2, 0, v15, vcc
	v_cndmask_b32_e32 v13, 0, v13, vcc
	v_cndmask_b32_e32 v12, 0, v12, vcc
	v_lshlrev_b32_e32 v20, 16, v12
	v_and_b32_e32 v21, 0xffff0000, v12
	v_lshlrev_b32_e32 v18, 16, v13
	v_and_b32_e32 v19, 0xffff0000, v13
	v_lshlrev_b32_e32 v12, 16, v2
	v_and_b32_e32 v13, 0xffff0000, v2
	v_add_u32_e32 v2, 6, v0
	v_cndmask_b32_e32 v3, 0, v14, vcc
	v_cmp_gt_u32_e32 vcc, s37, v2
	s_and_b64 vcc, s[40:41], vcc
	v_lshlrev_b32_e32 v14, 16, v3
	v_cndmask_b32_e32 v2, v1, v2, vcc
	v_mul_i32_i24_e32 v152, 0xd00, v2
	v_and_b32_e32 v15, 0xffff0000, v3
	v_lshl_add_u64 v[2:3], v[152:153], 1, v[16:17]
	v_mov_b32_e32 v22, v100
	v_mov_b32_e32 v23, v101
	v_mov_b32_e32 v24, v102
	v_mov_b32_e32 v25, v103
	v_pk_add_f32 v[8:9], v[8:9], v[18:19]
	v_pk_add_f32 v[6:7], v[6:7], v[14:15]
	v_pk_add_f32 v[4:5], v[4:5], v[12:13]
	s_waitcnt vmcnt(0)
	v_cndmask_b32_e32 v2, 0, v25, vcc
	v_cndmask_b32_e32 v23, 0, v23, vcc
	v_cndmask_b32_e32 v22, 0, v22, vcc
	v_lshlrev_b32_e32 v32, 16, v22
	v_and_b32_e32 v33, 0xffff0000, v22
	v_lshlrev_b32_e32 v28, 16, v23
	v_and_b32_e32 v29, 0xffff0000, v23
	v_lshlrev_b32_e32 v22, 16, v2
	v_and_b32_e32 v23, 0xffff0000, v2
	v_add_u32_e32 v2, 7, v0
	v_cndmask_b32_e32 v3, 0, v24, vcc
	v_cmp_gt_u32_e32 vcc, s37, v2
	s_and_b64 vcc, s[40:41], vcc
	v_lshlrev_b32_e32 v24, 16, v3
	v_cndmask_b32_e32 v2, v1, v2, vcc
	v_mul_i32_i24_e32 v152, 0xd00, v2
	v_and_b32_e32 v25, 0xffff0000, v3
	v_lshl_add_u64 v[2:3], v[152:153], 1, v[16:17]
	v_mov_b32_e32 v34, v104
	v_mov_b32_e32 v35, v105
	v_mov_b32_e32 v36, v106
	v_mov_b32_e32 v37, v107
	v_pk_add_f32 v[8:9], v[8:9], v[28:29]
	v_pk_add_f32 v[6:7], v[6:7], v[24:25]
	v_pk_add_f32 v[4:5], v[4:5], v[22:23]
	s_waitcnt vmcnt(0)
	v_cndmask_b32_e32 v2, 0, v37, vcc
	v_cndmask_b32_e32 v26, 0, v35, vcc
	v_cndmask_b32_e32 v27, 0, v34, vcc
	v_cndmask_b32_e32 v3, 0, v36, vcc
	v_lshlrev_b32_e32 v36, 16, v27
	v_and_b32_e32 v37, 0xffff0000, v27
	v_lshlrev_b32_e32 v34, 16, v26
	v_and_b32_e32 v35, 0xffff0000, v26
	v_lshlrev_b32_e32 v26, 16, v2
	v_and_b32_e32 v27, 0xffff0000, v2
	v_add_u32_e32 v2, 8, v0
	v_cndmask_b32_e64 v2, v1, v2, s[42:43]
	v_mul_i32_i24_e32 v152, 0xd00, v2
	v_lshlrev_b32_e32 v30, 16, v3
	v_and_b32_e32 v31, 0xffff0000, v3
	v_lshl_add_u64 v[2:3], v[152:153], 1, v[16:17]
	v_mov_b32_e32 v44, v108
	v_mov_b32_e32 v45, v109
	v_mov_b32_e32 v46, v110
	v_mov_b32_e32 v47, v111
	v_add_u32_e32 v2, 9, v0
	v_cndmask_b32_e64 v2, v1, v2, s[42:43]
	v_mul_i32_i24_e32 v152, 0xd00, v2
	v_lshl_add_u64 v[2:3], v[152:153], 1, v[16:17]
	v_mov_b32_e32 v48, v112
	v_mov_b32_e32 v49, v113
	v_mov_b32_e32 v50, v114
	v_mov_b32_e32 v51, v115
	v_add_u32_e32 v2, 10, v0
	v_cndmask_b32_e64 v2, v1, v2, s[42:43]
	v_mul_i32_i24_e32 v152, 0xd00, v2
	v_lshl_add_u64 v[2:3], v[152:153], 1, v[16:17]
	v_mov_b32_e32 v56, v116
	v_mov_b32_e32 v57, v117
	v_mov_b32_e32 v58, v118
	v_mov_b32_e32 v59, v119
	v_add_u32_e32 v2, 11, v0
	v_cndmask_b32_e64 v2, v1, v2, s[42:43]
	v_mul_i32_i24_e32 v152, 0xd00, v2
	v_lshl_add_u64 v[2:3], v[152:153], 1, v[16:17]
	v_pk_add_f32 v[8:9], v[8:9], v[34:35]
	v_pk_add_f32 v[6:7], v[6:7], v[30:31]
	v_pk_add_f32 v[4:5], v[4:5], v[26:27]
	s_waitcnt vmcnt(2)
	v_cndmask_b32_e64 v40, 0, v47, s[42:43]
	v_cndmask_b32_e64 v42, 0, v46, s[42:43]
	v_cndmask_b32_e64 v46, 0, v45, s[42:43]
	v_cndmask_b32_e64 v53, 0, v44, s[42:43]
	v_lshlrev_b32_e32 v14, 16, v42
	s_waitcnt vmcnt(1)
	v_cndmask_b32_e64 v41, 0, v51, s[42:43]
	v_cndmask_b32_e64 v62, 0, v48, s[42:43]
	v_cndmask_b32_e64 v44, 0, v50, s[42:43]
	v_cndmask_b32_e64 v50, 0, v49, s[42:43]
	v_and_b32_e32 v15, 0xffff0000, v42
	s_waitcnt vmcnt(0)
	v_cndmask_b32_e64 v43, 0, v59, s[42:43]
	v_cndmask_b32_e64 v47, 0, v58, s[42:43]
	v_cndmask_b32_e64 v54, 0, v57, s[42:43]
	v_cndmask_b32_e64 v63, 0, v56, s[42:43]
	v_mov_b32_e32 v56, v120
	v_mov_b32_e32 v57, v121
	v_mov_b32_e32 v58, v122
	v_mov_b32_e32 v59, v123
	v_add_u32_e32 v2, 12, v0
	v_cndmask_b32_e64 v2, v1, v2, s[42:43]
	v_mul_i32_i24_e32 v152, 0xd00, v2
	v_lshl_add_u64 v[2:3], v[152:153], 1, v[16:17]
	v_lshlrev_b32_e32 v12, 16, v40
	v_and_b32_e32 v13, 0xffff0000, v40
	v_pk_add_f32 v[6:7], v[6:7], v[14:15]
	v_lshlrev_b32_e32 v14, 16, v44
	v_and_b32_e32 v15, 0xffff0000, v44
	v_pk_add_f32 v[4:5], v[4:5], v[12:13]
	v_lshlrev_b32_e32 v12, 16, v41
	v_and_b32_e32 v13, 0xffff0000, v41
	v_pk_add_f32 v[6:7], v[6:7], v[14:15]
	v_lshlrev_b32_e32 v14, 16, v47
	v_and_b32_e32 v15, 0xffff0000, v47
	v_pk_add_f32 v[4:5], v[4:5], v[12:13]
	v_lshlrev_b32_e32 v12, 16, v43
	v_and_b32_e32 v13, 0xffff0000, v43
	v_pk_add_f32 v[6:7], v[6:7], v[14:15]
	v_pk_add_f32 v[4:5], v[4:5], v[12:13]
	s_waitcnt vmcnt(0)
	v_cndmask_b32_e64 v45, 0, v59, s[42:43]
	v_cndmask_b32_e64 v51, 0, v58, s[42:43]
	v_cndmask_b32_e64 v64, 0, v57, s[42:43]
	v_cndmask_b32_e64 v65, 0, v56, s[42:43]
	v_mov_b32_e32 v56, v124
	v_mov_b32_e32 v57, v125
	v_mov_b32_e32 v58, v126
	v_mov_b32_e32 v59, v127
	v_add_u32_e32 v2, 13, v0
	v_cndmask_b32_e64 v2, v1, v2, s[42:43]
	v_mul_i32_i24_e32 v152, 0xd00, v2
	v_lshl_add_u64 v[2:3], v[152:153], 1, v[16:17]
	v_lshlrev_b32_e32 v14, 16, v51
	v_and_b32_e32 v15, 0xffff0000, v51
	v_lshlrev_b32_e32 v12, 16, v45
	v_and_b32_e32 v13, 0xffff0000, v45
	v_pk_add_f32 v[6:7], v[6:7], v[14:15]
	v_pk_add_f32 v[4:5], v[4:5], v[12:13]
	s_waitcnt vmcnt(0)
	v_cndmask_b32_e64 v48, 0, v59, s[42:43]
	v_cndmask_b32_e64 v55, 0, v58, s[42:43]
	v_mov_b32_e32 v58, v128
	v_mov_b32_e32 v59, v129
	v_mov_b32_e32 v60, v130
	v_mov_b32_e32 v61, v131
	v_add_u32_e32 v2, 14, v0
	v_cndmask_b32_e64 v2, v1, v2, s[42:43]
	v_add_u32_e32 v0, 15, v0
	v_mul_i32_i24_e32 v152, 0xd00, v2
	v_cndmask_b32_e64 v0, v1, v0, s[42:43]
	v_lshl_add_u64 v[2:3], v[152:153], 1, v[16:17]
	v_mul_i32_i24_e32 v152, 0xd00, v0
	v_lshl_add_u64 v[0:1], v[152:153], 1, v[16:17]
	v_cndmask_b32_e64 v66, 0, v56, s[42:43]
	v_cndmask_b32_e64 v57, 0, v57, s[42:43]
	v_lshlrev_b32_e32 v14, 16, v55
	v_and_b32_e32 v15, 0xffff0000, v55
	v_lshlrev_b32_e32 v12, 16, v48
	v_and_b32_e32 v13, 0xffff0000, v48
	v_pk_add_f32 v[6:7], v[6:7], v[14:15]
	v_pk_add_f32 v[4:5], v[4:5], v[12:13]
	s_waitcnt vmcnt(0)
	v_cndmask_b32_e64 v49, 0, v61, s[42:43]
	v_cndmask_b32_e64 v56, 0, v60, s[42:43]
	v_cndmask_b32_e64 v67, 0, v59, s[42:43]
	v_cndmask_b32_e64 v68, 0, v58, s[42:43]
	v_mov_b32_e32 v58, v132
	v_mov_b32_e32 v59, v133
	v_mov_b32_e32 v60, v134
	v_mov_b32_e32 v61, v135
	v_lshlrev_b32_e32 v14, 16, v56
	v_mov_b32_e32 v0, v136
	v_mov_b32_e32 v1, v137
	v_mov_b32_e32 v2, v138
	v_mov_b32_e32 v3, v139
	v_and_b32_e32 v15, 0xffff0000, v56
	v_lshlrev_b32_e32 v12, 16, v49
	v_and_b32_e32 v13, 0xffff0000, v49
	v_pk_add_f32 v[6:7], v[6:7], v[14:15]
	v_pk_add_f32 v[4:5], v[4:5], v[12:13]
	s_waitcnt vmcnt(1)
	v_cndmask_b32_e64 v52, 0, v61, s[42:43]
	v_cndmask_b32_e64 v60, 0, v60, s[42:43]
	s_waitcnt vmcnt(0)
	v_cndmask_b32_e64 v70, 0, v1, s[42:43]
	v_cndmask_b32_e64 v71, 0, v0, s[42:43]
	v_pk_add_f32 v[0:1], v[10:11], v[20:21]
	v_cndmask_b32_e64 v61, 0, v3, s[42:43]
	v_pk_add_f32 v[0:1], v[0:1], v[32:33]
	v_cndmask_b32_e64 v69, 0, v2, s[42:43]
	v_pk_add_f32 v[0:1], v[0:1], v[36:37]
	v_lshlrev_b32_e32 v2, 16, v53
	v_and_b32_e32 v3, 0xffff0000, v53
	v_lshlrev_b32_e32 v10, 16, v46
	v_and_b32_e32 v11, 0xffff0000, v46
	v_pk_add_f32 v[0:1], v[0:1], v[2:3]
	v_lshlrev_b32_e32 v2, 16, v62
	v_and_b32_e32 v3, 0xffff0000, v62
	v_pk_add_f32 v[8:9], v[8:9], v[10:11]
	v_lshlrev_b32_e32 v10, 16, v50
	v_and_b32_e32 v11, 0xffff0000, v50
	v_pk_add_f32 v[0:1], v[0:1], v[2:3]
	v_lshlrev_b32_e32 v2, 16, v63
	v_and_b32_e32 v3, 0xffff0000, v63
	v_pk_add_f32 v[8:9], v[8:9], v[10:11]
	v_lshlrev_b32_e32 v10, 16, v54
	v_and_b32_e32 v11, 0xffff0000, v54
	v_pk_add_f32 v[0:1], v[0:1], v[2:3]
	v_lshlrev_b32_e32 v2, 16, v65
	v_and_b32_e32 v3, 0xffff0000, v65
	v_pk_add_f32 v[8:9], v[8:9], v[10:11]
	v_lshlrev_b32_e32 v10, 16, v64
	v_and_b32_e32 v11, 0xffff0000, v64
	v_pk_add_f32 v[0:1], v[0:1], v[2:3]
	v_lshlrev_b32_e32 v2, 16, v66
	v_and_b32_e32 v3, 0xffff0000, v66
	v_pk_add_f32 v[8:9], v[8:9], v[10:11]
	v_lshlrev_b32_e32 v10, 16, v57
	v_and_b32_e32 v11, 0xffff0000, v57
	v_cndmask_b32_e64 v59, 0, v59, s[42:43]
	v_cndmask_b32_e64 v58, 0, v58, s[42:43]
	v_pk_add_f32 v[0:1], v[0:1], v[2:3]
	v_lshlrev_b32_e32 v2, 16, v68
	v_and_b32_e32 v3, 0xffff0000, v68
	v_pk_add_f32 v[8:9], v[8:9], v[10:11]
	v_lshlrev_b32_e32 v10, 16, v67
	v_and_b32_e32 v11, 0xffff0000, v67
	v_pk_add_f32 v[0:1], v[0:1], v[2:3]
	v_lshlrev_b32_e32 v2, 16, v58
	v_and_b32_e32 v3, 0xffff0000, v58
	v_pk_add_f32 v[8:9], v[8:9], v[10:11]
	v_lshlrev_b32_e32 v10, 16, v59
	v_and_b32_e32 v11, 0xffff0000, v59
	v_lshlrev_b32_e32 v14, 16, v60
	v_and_b32_e32 v15, 0xffff0000, v60
	v_lshlrev_b32_e32 v12, 16, v52
	v_and_b32_e32 v13, 0xffff0000, v52
	v_pk_add_f32 v[0:1], v[0:1], v[2:3]
	v_lshlrev_b32_e32 v2, 16, v71
	v_and_b32_e32 v3, 0xffff0000, v71
	v_pk_add_f32 v[8:9], v[8:9], v[10:11]
	v_lshlrev_b32_e32 v10, 16, v70
	v_and_b32_e32 v11, 0xffff0000, v70
	v_pk_add_f32 v[6:7], v[6:7], v[14:15]
	v_lshlrev_b32_e32 v14, 16, v69
	v_and_b32_e32 v15, 0xffff0000, v69
	v_pk_add_f32 v[4:5], v[4:5], v[12:13]
	v_lshlrev_b32_e32 v12, 16, v61
	v_and_b32_e32 v13, 0xffff0000, v61
	v_pk_add_f32 v[18:19], v[0:1], v[2:3]
	v_pk_add_f32 v[22:23], v[8:9], v[10:11]
	v_pk_add_f32 v[20:21], v[6:7], v[14:15]
	v_pk_add_f32 v[24:25], v[4:5], v[12:13]
.LBB0_613:
	v_mov_b32_e32 v143, 0
	v_lshl_add_u64 v[144:145], s[16:17], 0, v[154:155]
	v_add_co_u32_e32 v144, vcc, 0xa400000, v144
	s_nop 1
	v_addc_co_u32_e32 v145, vcc, 0, v145, vcc
	s_add_i32 s21, s1, s18
	s_add_i32 s21, s21, 4
	v_mov_b32_e32 v141, s21
	global_load_dwordx4 v[76:79], v[144:145], off offset:1536
	v_add_u32_e32 v140, s18, v38
	v_add_u32_e32 v140, 4, v140
	v_cmp_gt_u32_e32 vcc, s37, v140
	s_nop 1
	v_cndmask_b32_e32 v140, v141, v140, vcc
	v_mul_lo_u32 v142, v140, s55
	v_lshl_add_u64 v[146:147], v[142:143], 1, v[16:17]
	global_load_dwordx4 v[80:83], v[146:147], off offset:1536
	v_add_u32_e32 v140, s18, v39
	v_add_u32_e32 v140, 4, v140
	v_cmp_gt_i32_e32 vcc, 0, v140
	s_nop 1
	v_cndmask_b32_e32 v140, v140, v141, vcc
	v_mul_lo_u32 v148, v140, s55
	v_ashrrev_i32_e32 v149, 31, v148
	v_lshl_add_u64 v[146:147], v[148:149], 1, v[16:17]
	global_load_dwordx4 v[84:87], v[146:147], off offset:1536
	s_add_i32 s21, s1, s18
	s_add_i32 s21, s21, 5
	v_mov_b32_e32 v141, s21
	v_add_co_u32_e32 v146, vcc, 0x1a00, v144
	s_nop 1
	v_addc_co_u32_e32 v147, vcc, 0, v145, vcc
	global_load_dwordx4 v[88:91], v[146:147], off offset:1536
	v_add_u32_e32 v140, s18, v38
	v_add_u32_e32 v140, 5, v140
	v_cmp_gt_u32_e32 vcc, s37, v140
	s_nop 1
	v_cndmask_b32_e32 v140, v141, v140, vcc
	v_mul_lo_u32 v142, v140, s55
	v_lshl_add_u64 v[146:147], v[142:143], 1, v[16:17]
	global_load_dwordx4 v[92:95], v[146:147], off offset:1536
	v_add_u32_e32 v140, s18, v39
	v_add_u32_e32 v140, 5, v140
	v_cmp_gt_i32_e32 vcc, 0, v140
	s_nop 1
	v_cndmask_b32_e32 v140, v140, v141, vcc
	v_mul_lo_u32 v148, v140, s55
	v_ashrrev_i32_e32 v149, 31, v148
	v_lshl_add_u64 v[146:147], v[148:149], 1, v[16:17]
	global_load_dwordx4 v[96:99], v[146:147], off offset:1536
	s_add_i32 s21, s1, s18
	s_add_i32 s21, s21, 6
	v_mov_b32_e32 v141, s21
	v_add_co_u32_e32 v146, vcc, 0x3400, v144
	s_nop 1
	v_addc_co_u32_e32 v147, vcc, 0, v145, vcc
	global_load_dwordx4 v[100:103], v[146:147], off offset:1536
	v_add_u32_e32 v140, s18, v38
	v_add_u32_e32 v140, 6, v140
	v_cmp_gt_u32_e32 vcc, s37, v140
	s_nop 1
	v_cndmask_b32_e32 v140, v141, v140, vcc
	v_mul_lo_u32 v142, v140, s55
	v_lshl_add_u64 v[146:147], v[142:143], 1, v[16:17]
	global_load_dwordx4 v[104:107], v[146:147], off offset:1536
	v_add_u32_e32 v140, s18, v39
	v_add_u32_e32 v140, 6, v140
	v_cmp_gt_i32_e32 vcc, 0, v140
	s_nop 1
	v_cndmask_b32_e32 v140, v140, v141, vcc
	v_mul_lo_u32 v148, v140, s55
	v_ashrrev_i32_e32 v149, 31, v148
	v_lshl_add_u64 v[146:147], v[148:149], 1, v[16:17]
	global_load_dwordx4 v[108:111], v[146:147], off offset:1536
	s_add_i32 s21, s1, s18
	s_add_i32 s21, s21, 7
	v_mov_b32_e32 v141, s21
	v_add_co_u32_e32 v146, vcc, 0x4e00, v144
	s_nop 1
	v_addc_co_u32_e32 v147, vcc, 0, v145, vcc
	global_load_dwordx4 v[112:115], v[146:147], off offset:1536
	v_add_u32_e32 v140, s18, v38
	v_add_u32_e32 v140, 7, v140
	v_cmp_gt_u32_e32 vcc, s37, v140
	s_nop 1
	v_cndmask_b32_e32 v140, v141, v140, vcc
	v_mul_lo_u32 v142, v140, s55
	v_lshl_add_u64 v[146:147], v[142:143], 1, v[16:17]
	global_load_dwordx4 v[116:119], v[146:147], off offset:1536
	v_add_u32_e32 v140, s18, v39
	v_add_u32_e32 v140, 7, v140
	v_cmp_gt_i32_e32 vcc, 0, v140
	s_nop 1
	v_cndmask_b32_e32 v140, v140, v141, vcc
	v_mul_lo_u32 v148, v140, s55
	v_ashrrev_i32_e32 v149, 31, v148
	v_lshl_add_u64 v[146:147], v[148:149], 1, v[16:17]
	global_load_dwordx4 v[120:123], v[146:147], off offset:1536
	s_waitcnt vmcnt(0)
	v_lshl_add_u64 v[28:29], s[16:17], 0, v[154:155]
	s_add_i32 s19, s1, s18
	v_add_u32_e32 v26, s18, v38
	v_add_co_u32_e32 v0, vcc, 0xa400000, v28
	s_add_i32 s20, s19, 4
	v_add_u32_e32 v72, 4, v26
	v_addc_co_u32_e32 v1, vcc, 0, v29, vcc
	v_cmp_gt_u32_e32 vcc, s37, v72
	v_mov_b32_e32 v4, s20
	v_mov_b32_e32 v12, v76
	v_mov_b32_e32 v13, v77
	v_mov_b32_e32 v14, v78
	v_mov_b32_e32 v15, v79
	v_cndmask_b32_e32 v0, v4, v72, vcc
	v_mul_lo_u32 v152, v0, s55
	v_lshl_add_u64 v[0:1], v[152:153], 1, v[16:17]
	v_mov_b32_e32 v0, v80
	v_mov_b32_e32 v1, v81
	v_mov_b32_e32 v2, v82
	v_mov_b32_e32 v3, v83
	v_add_u32_e32 v41, s18, v39
	v_add_u32_e32 v73, 4, v41
	s_mov_b32 s21, 0xa402000
	s_add_i32 s20, s19, 5
	v_add_u32_e32 v57, 5, v26
	v_mov_b32_e32 v8, s20
	v_add_u32_e32 v58, 5, v41
	s_add_i32 s20, s19, 6
	v_add_u32_e32 v62, 6, v26
	v_mov_b32_e32 v36, s20
	v_add_u32_e32 v63, 6, v41
	s_mov_b32 s20, 0xa405000
	s_add_i32 s19, s19, 7
	v_add_u32_e32 v65, 7, v26
	v_mov_b32_e32 v26, s19
	v_add_u32_e32 v66, 7, v41
	s_mov_b32 s19, 0x1d400000
	s_add_i32 s18, s18, 4
	s_waitcnt vmcnt(0)
	v_cndmask_b32_e32 v27, 0, v3, vcc
	v_cndmask_b32_e32 v32, 0, v2, vcc
	v_cndmask_b32_e32 v42, 0, v1, vcc
	v_cndmask_b32_e32 v47, 0, v0, vcc
	v_cmp_gt_i32_e32 vcc, 0, v73
	s_nop 1
	v_cndmask_b32_e32 v0, v73, v4, vcc
	v_mul_lo_u32 v0, v0, s55
	v_ashrrev_i32_e32 v1, 31, v0
	v_lshl_add_u64 v[0:1], v[0:1], 1, v[16:17]
	v_mov_b32_e32 v0, v84
	v_mov_b32_e32 v1, v85
	v_mov_b32_e32 v2, v86
	v_mov_b32_e32 v3, v87
	s_waitcnt vmcnt(0)
	v_cndmask_b32_e64 v30, v3, 0, vcc
	v_cndmask_b32_e64 v34, v2, 0, vcc
	v_cndmask_b32_e64 v45, v1, 0, vcc
	v_cndmask_b32_e64 v48, v0, 0, vcc
	v_add_co_u32_e32 v0, vcc, s21, v28
	s_mov_b32 s21, 0xa403000
	s_nop 0
	v_addc_co_u32_e32 v1, vcc, 0, v29, vcc
	v_cmp_gt_u32_e32 vcc, s37, v57
	v_mov_b32_e32 v0, v88
	v_mov_b32_e32 v1, v89
	v_mov_b32_e32 v2, v90
	v_mov_b32_e32 v3, v91
	s_nop 0
	v_cndmask_b32_e32 v4, v8, v57, vcc
	v_mul_lo_u32 v152, v4, s55
	v_lshl_add_u64 v[4:5], v[152:153], 1, v[16:17]
	v_mov_b32_e32 v4, v92
	v_mov_b32_e32 v5, v93
	v_mov_b32_e32 v6, v94
	v_mov_b32_e32 v7, v95
	s_waitcnt vmcnt(0)
	v_cndmask_b32_e32 v31, 0, v7, vcc
	v_cndmask_b32_e32 v37, 0, v6, vcc
	v_cndmask_b32_e32 v49, 0, v5, vcc
	v_cndmask_b32_e32 v55, 0, v4, vcc
	v_cmp_gt_i32_e32 vcc, 0, v58
	s_nop 1
	v_cndmask_b32_e32 v4, v58, v8, vcc
	v_mul_lo_u32 v4, v4, s55
	v_ashrrev_i32_e32 v5, 31, v4
	v_lshl_add_u64 v[4:5], v[4:5], 1, v[16:17]
	v_mov_b32_e32 v4, v96
	v_mov_b32_e32 v5, v97
	v_mov_b32_e32 v6, v98
	v_mov_b32_e32 v7, v99
	s_waitcnt vmcnt(0)
	v_cndmask_b32_e64 v33, v7, 0, vcc
	v_cndmask_b32_e64 v40, v6, 0, vcc
	v_cndmask_b32_e64 v51, v5, 0, vcc
	v_cndmask_b32_e64 v56, v4, 0, vcc
	v_add_co_u32_e32 v4, vcc, s21, v28
	s_nop 1
	v_addc_co_u32_e32 v5, vcc, 0, v29, vcc
	v_cmp_gt_u32_e32 vcc, s37, v62
	v_mov_b32_e32 v4, v100
	v_mov_b32_e32 v5, v101
	v_mov_b32_e32 v6, v102
	v_mov_b32_e32 v7, v103
	s_nop 0
	v_cndmask_b32_e32 v8, v36, v62, vcc
	v_mul_lo_u32 v152, v8, s55
	v_lshl_add_u64 v[8:9], v[152:153], 1, v[16:17]
	v_mov_b32_e32 v8, v104
	v_mov_b32_e32 v9, v105
	v_mov_b32_e32 v10, v106
	v_mov_b32_e32 v11, v107
	s_waitcnt vmcnt(0)
	v_cndmask_b32_e32 v35, 0, v11, vcc
	v_cndmask_b32_e32 v44, 0, v10, vcc
	v_cndmask_b32_e32 v53, 0, v9, vcc
	v_cndmask_b32_e32 v61, 0, v8, vcc
	v_cmp_gt_i32_e32 vcc, 0, v63
	s_nop 1
	v_cndmask_b32_e32 v8, v63, v36, vcc
	v_mul_lo_u32 v8, v8, s55
	v_ashrrev_i32_e32 v9, 31, v8
	v_lshl_add_u64 v[8:9], v[8:9], 1, v[16:17]
	v_mov_b32_e32 v8, v108
	v_mov_b32_e32 v9, v109
	v_mov_b32_e32 v10, v110
	v_mov_b32_e32 v11, v111
	s_waitcnt vmcnt(0)
	v_cndmask_b32_e64 v36, v11, 0, vcc
	v_cndmask_b32_e64 v46, v10, 0, vcc
	v_cndmask_b32_e64 v54, v9, 0, vcc
	v_cndmask_b32_e64 v64, v8, 0, vcc
	v_add_co_u32_e32 v8, vcc, s20, v28
	s_nop 1
	v_addc_co_u32_e32 v9, vcc, 0, v29, vcc
	v_cmp_gt_u32_e32 vcc, s37, v65
	v_mov_b32_e32 v8, v112
	v_mov_b32_e32 v9, v113
	v_mov_b32_e32 v10, v114
	v_mov_b32_e32 v11, v115
	s_nop 0
	v_cndmask_b32_e32 v28, v26, v65, vcc
	v_mul_lo_u32 v152, v28, s55
	v_lshl_add_u64 v[28:29], v[152:153], 1, v[16:17]
	v_mov_b32_e32 v68, v116
	v_mov_b32_e32 v69, v117
	v_mov_b32_e32 v70, v118
	v_mov_b32_e32 v71, v119
	s_waitcnt vmcnt(0)
	v_cndmask_b32_e32 v41, 0, v71, vcc
	v_cndmask_b32_e32 v50, 0, v70, vcc
	v_cndmask_b32_e32 v59, 0, v69, vcc
	v_cndmask_b32_e32 v67, 0, v68, vcc
	v_cmp_gt_i32_e32 vcc, 0, v66
	s_nop 1
	v_cndmask_b32_e32 v26, v66, v26, vcc
	v_mul_lo_u32 v28, v26, s55
	v_ashrrev_i32_e32 v29, 31, v28
	v_lshl_add_u64 v[28:29], v[28:29], 1, v[16:17]
	v_mov_b32_e32 v68, v120
	v_mov_b32_e32 v69, v121
	v_mov_b32_e32 v70, v122
	v_mov_b32_e32 v71, v123
	v_max_i32_e32 v26, 0, v73
	v_min_u32_e32 v28, 0x2000, v72
	v_sub_u32_e32 v26, v28, v26
	v_cvt_f32_i32_e32 v26, v26
	v_mov_b32_e32 v72, v20
	v_mov_b32_e32 v73, v24
	v_div_scale_f32 v28, s[20:21], v26, v26, 1.0
	v_rcp_f32_e32 v29, v28
	s_waitcnt vmcnt(0)
	v_cndmask_b32_e64 v60, v69, 0, vcc
	v_fma_f32 v69, -v28, v29, 1.0
	v_cndmask_b32_e64 v43, v71, 0, vcc
	v_cndmask_b32_e64 v52, v70, 0, vcc
	v_cndmask_b32_e64 v68, v68, 0, vcc
	v_fmac_f32_e32 v29, v69, v29
	v_div_scale_f32 v69, vcc, 1.0, v26, 1.0
	v_mul_f32_e32 v70, v69, v29
	v_fma_f32 v71, -v28, v70, v69
	v_fmac_f32_e32 v70, v71, v29
	v_fma_f32 v28, -v28, v70, v69
	v_div_fmas_f32 v28, v28, v29, v70
	v_div_fixup_f32 v26, v28, v26, 1.0
	v_lshlrev_b32_e32 v29, 16, v13
	v_lshlrev_b32_e32 v28, 16, v12
	v_mov_b32_e32 v70, v18
	v_mov_b32_e32 v71, v22
	v_and_b32_e32 v13, 0xffff0000, v13
	v_and_b32_e32 v12, 0xffff0000, v12
	v_pk_fma_f32 v[28:29], v[70:71], v[26:27], v[28:29] op_sel_hi:[1,0,1] neg_lo:[0,0,1] neg_hi:[0,0,1]
	v_mov_b32_e32 v70, v19
	v_mov_b32_e32 v71, v23
	v_pk_fma_f32 v[12:13], v[70:71], v[26:27], v[12:13] op_sel_hi:[1,0,1] neg_lo:[0,0,1] neg_hi:[0,0,1]
	v_lshlrev_b32_e32 v71, 16, v15
	v_lshlrev_b32_e32 v70, 16, v14
	v_and_b32_e32 v15, 0xffff0000, v15
	v_and_b32_e32 v14, 0xffff0000, v14
	v_pk_fma_f32 v[70:71], v[72:73], v[26:27], v[70:71] op_sel_hi:[1,0,1] neg_lo:[0,0,1] neg_hi:[0,0,1]
	v_mov_b32_e32 v72, v21
	v_mov_b32_e32 v73, v25
	v_pk_fma_f32 v[14:15], v[72:73], v[26:27], v[14:15] op_sel_hi:[1,0,1] neg_lo:[0,0,1] neg_hi:[0,0,1]
	v_bfe_u32 v72, v13, 16, 1
	v_bfe_u32 v69, v14, 16, 1
	v_bfe_u32 v73, v12, 16, 1
	v_bfe_u32 v26, v15, 16, 1
	v_add3_u32 v12, v12, v73, s54
	v_add3_u32 v13, v13, v72, s54
	v_add3_u32 v14, v14, v69, s54
	v_bfe_u32 v69, v29, 16, 1
	v_bfe_u32 v72, v70, 16, 1
	v_bfe_u32 v73, v71, 16, 1
	v_add3_u32 v15, v15, v26, s54
	v_bfe_u32 v26, v28, 16, 1
	v_add3_u32 v71, v71, v73, s54
	v_add3_u32 v70, v70, v72, s54
	v_add3_u32 v29, v29, v69, s54
	v_add3_u32 v26, v28, v26, s54
	v_lshrrev_b32_e32 v28, 16, v29
	v_lshrrev_b32_e32 v29, 16, v70
	v_lshrrev_b32_e32 v69, 16, v71
	v_and_or_b32 v73, v15, s52, v69
	v_and_or_b32 v72, v14, s52, v29
	v_max_i32_e32 v14, 0, v58
	v_min_u32_e32 v15, 0x2000, v57
	v_sub_u32_e32 v14, v15, v14
	v_cvt_f32_i32_e32 v14, v14
	v_lshrrev_b32_e32 v26, 16, v26
	v_and_or_b32 v70, v12, s52, v26
	v_and_or_b32 v71, v13, s52, v28
	v_div_scale_f32 v15, s[20:21], v14, v14, 1.0
	v_rcp_f32_e32 v26, v15
	v_lshl_add_u64 v[12:13], s[10:11], 0, v[154:155]
	v_add_co_u32_e32 v12, vcc, s19, v12
	v_fma_f32 v28, -v15, v26, 1.0
	s_nop 0
	v_addc_co_u32_e32 v13, vcc, 0, v13, vcc
	v_fmac_f32_e32 v26, v28, v26
	v_div_scale_f32 v28, vcc, 1.0, v14, 1.0
	v_mul_f32_e32 v29, v28, v26
	v_fma_f32 v57, -v15, v29, v28
	v_fmac_f32_e32 v29, v57, v26
	v_fma_f32 v15, -v15, v29, v28
	v_div_fmas_f32 v15, v15, v26, v29
	v_div_fixup_f32 v14, v15, v14, 1.0
	v_max_i32_e32 v15, 0, v63
	v_min_u32_e32 v26, 0x2000, v62
	v_sub_u32_e32 v15, v26, v15
	v_cvt_f32_i32_e32 v15, v15
	global_store_dwordx4 v[12:13], v[70:73], off
	v_and_b32_e32 v63, 0xffff0000, v47
	v_and_b32_e32 v69, 0xffff0000, v45
	v_div_scale_f32 v26, s[20:21], v15, v15, 1.0
	v_rcp_f32_e32 v28, v26
	v_lshlrev_b32_e32 v70, 16, v48
	v_and_b32_e32 v71, 0xffff0000, v48
	v_lshlrev_b32_e32 v48, 16, v49
	v_fma_f32 v29, -v26, v28, 1.0
	v_fmac_f32_e32 v28, v29, v28
	v_div_scale_f32 v29, vcc, 1.0, v15, 1.0
	v_mul_f32_e32 v57, v29, v28
	v_fma_f32 v58, -v26, v57, v29
	v_fmac_f32_e32 v57, v58, v28
	v_fma_f32 v26, -v26, v57, v29
	v_div_fmas_f32 v26, v26, v28, v57
	v_div_fixup_f32 v26, v26, v15, 1.0
	v_max_i32_e32 v15, 0, v66
	v_min_u32_e32 v28, 0x2000, v65
	v_sub_u32_e32 v15, v28, v15
	v_cvt_f32_i32_e32 v15, v15
	v_lshlrev_b32_e32 v66, 16, v68
	v_and_b32_e32 v49, 0xffff0000, v49
	s_add_u32 s10, s10, 0x1000
	v_div_scale_f32 v28, s[20:21], v15, v15, 1.0
	v_rcp_f32_e32 v29, v28
	s_addc_u32 s11, s11, 0
	s_add_u32 s16, s16, 0x6800
	s_addc_u32 s17, s17, 0
	v_fma_f32 v57, -v28, v29, 1.0
	v_fmac_f32_e32 v29, v57, v29
	v_div_scale_f32 v57, vcc, 1.0, v15, 1.0
	v_mul_f32_e32 v58, v57, v29
	v_fma_f32 v62, -v28, v58, v57
	v_fmac_f32_e32 v58, v62, v29
	v_lshlrev_b32_e32 v62, 16, v47
	v_pk_add_f32 v[62:63], v[62:63], v[70:71] neg_lo:[0,1] neg_hi:[0,1]
	v_lshlrev_b32_e32 v70, 16, v56
	v_pk_add_f32 v[62:63], v[18:19], v[62:63]
	v_lshlrev_b32_e32 v18, 16, v55
	v_and_b32_e32 v19, 0xffff0000, v55
	v_and_b32_e32 v71, 0xffff0000, v56
	v_pk_add_f32 v[18:19], v[18:19], v[70:71] neg_lo:[0,1] neg_hi:[0,1]
	v_fma_f32 v28, -v28, v58, v57
	v_pk_add_f32 v[56:57], v[62:63], v[18:19]
	v_lshlrev_b32_e32 v18, 16, v61
	v_and_b32_e32 v19, 0xffff0000, v61
	v_lshlrev_b32_e32 v70, 16, v64
	v_and_b32_e32 v71, 0xffff0000, v64
	v_pk_add_f32 v[18:19], v[18:19], v[70:71] neg_lo:[0,1] neg_hi:[0,1]
	v_div_fmas_f32 v28, v28, v29, v58
	v_pk_add_f32 v[64:65], v[56:57], v[18:19]
	v_lshlrev_b32_e32 v18, 16, v67
	v_and_b32_e32 v19, 0xffff0000, v67
	v_and_b32_e32 v67, 0xffff0000, v68
	v_pk_add_f32 v[18:19], v[18:19], v[66:67] neg_lo:[0,1] neg_hi:[0,1]
	v_lshlrev_b32_e32 v66, 16, v42
	v_and_b32_e32 v67, 0xffff0000, v42
	v_lshlrev_b32_e32 v68, 16, v45
	v_pk_add_f32 v[66:67], v[66:67], v[68:69] neg_lo:[0,1] neg_hi:[0,1]
	v_mov_b32_e32 v68, v62
	v_pk_add_f32 v[22:23], v[22:23], v[66:67]
	v_lshlrev_b32_e32 v67, 16, v1
	v_lshlrev_b32_e32 v66, 16, v0
	v_and_b32_e32 v1, 0xffff0000, v1
	v_and_b32_e32 v0, 0xffff0000, v0
	v_mov_b32_e32 v62, v63
	v_mov_b32_e32 v63, v23
	v_pk_fma_f32 v[0:1], v[14:15], v[62:63], v[0:1] op_sel_hi:[0,1,1] neg_lo:[0,0,1] neg_hi:[0,0,1]
	v_lshlrev_b32_e32 v62, 16, v51
	v_and_b32_e32 v63, 0xffff0000, v51
	v_pk_add_f32 v[48:49], v[48:49], v[62:63] neg_lo:[0,1] neg_hi:[0,1]
	v_mov_b32_e32 v69, v22
	v_pk_add_f32 v[22:23], v[22:23], v[48:49]
	v_lshlrev_b32_e32 v49, 16, v5
	v_lshlrev_b32_e32 v48, 16, v4
	v_mov_b32_e32 v62, v56
	v_mov_b32_e32 v63, v22
	v_pk_fma_f32 v[48:49], v[26:27], v[62:63], v[48:49] op_sel_hi:[0,1,1] neg_lo:[0,0,1] neg_hi:[0,0,1]
	v_div_fixup_f32 v28, v28, v15, 1.0
	v_pk_fma_f32 v[66:67], v[14:15], v[68:69], v[66:67] op_sel_hi:[0,1,1] neg_lo:[0,0,1] neg_hi:[0,0,1]
	v_and_b32_e32 v5, 0xffff0000, v5
	v_and_b32_e32 v4, 0xffff0000, v4
	v_mov_b32_e32 v56, v57
	v_mov_b32_e32 v57, v23
	v_and_b32_sdwa v15, v49, v203 dst_sel:DWORD dst_unused:UNUSED_PAD src0_sel:WORD_1 src1_sel:DWORD
	v_and_b32_sdwa v29, v48, v203 dst_sel:DWORD dst_unused:UNUSED_PAD src0_sel:WORD_1 src1_sel:DWORD
	v_pk_fma_f32 v[4:5], v[26:27], v[56:57], v[4:5] op_sel_hi:[0,1,1] neg_lo:[0,0,1] neg_hi:[0,0,1]
	v_add3_u32 v29, v48, v29, s54
	v_add3_u32 v15, v49, v15, s54
	v_lshlrev_b32_e32 v48, 16, v53
	v_and_b32_e32 v49, 0xffff0000, v53
	v_lshlrev_b32_e32 v56, 16, v54
	v_and_b32_e32 v57, 0xffff0000, v54
	v_pk_add_f32 v[48:49], v[48:49], v[56:57] neg_lo:[0,1] neg_hi:[0,1]
	v_and_b32_sdwa v42, v5, v203 dst_sel:DWORD dst_unused:UNUSED_PAD src0_sel:WORD_1 src1_sel:DWORD
	v_and_b32_sdwa v45, v4, v203 dst_sel:DWORD dst_unused:UNUSED_PAD src0_sel:WORD_1 src1_sel:DWORD
	v_pk_add_f32 v[22:23], v[22:23], v[48:49]
	v_add3_u32 v5, v5, v42, s54
	v_add3_u32 v4, v4, v45, s54
	v_lshlrev_b32_e32 v49, 16, v9
	v_lshlrev_b32_e32 v48, 16, v8
	v_mov_b32_e32 v54, v64
	v_mov_b32_e32 v55, v22
	v_and_b32_e32 v5, 0xffff0000, v5
	v_and_b32_e32 v4, 0xffff0000, v4
	v_and_b32_e32 v9, 0xffff0000, v9
	v_and_b32_e32 v8, 0xffff0000, v8
	v_pk_fma_f32 v[48:49], v[28:29], v[54:55], v[48:49] op_sel_hi:[0,1,1] neg_lo:[0,0,1] neg_hi:[0,0,1]
	v_mov_b32_e32 v54, v65
	v_mov_b32_e32 v55, v23
	v_or_b32_sdwa v5, v5, v15 dst_sel:DWORD dst_unused:UNUSED_PAD src0_sel:DWORD src1_sel:WORD_1
	v_or_b32_sdwa v4, v4, v29 dst_sel:DWORD dst_unused:UNUSED_PAD src0_sel:DWORD src1_sel:WORD_1
	v_pk_fma_f32 v[8:9], v[28:29], v[54:55], v[8:9] op_sel_hi:[0,1,1] neg_lo:[0,0,1] neg_hi:[0,0,1]
	v_and_b32_sdwa v15, v49, v203 dst_sel:DWORD dst_unused:UNUSED_PAD src0_sel:WORD_1 src1_sel:DWORD
	v_and_b32_sdwa v29, v48, v203 dst_sel:DWORD dst_unused:UNUSED_PAD src0_sel:WORD_1 src1_sel:DWORD
	v_add3_u32 v29, v48, v29, s54
	v_add3_u32 v15, v49, v15, s54
	v_lshlrev_b32_e32 v48, 16, v59
	v_and_b32_e32 v49, 0xffff0000, v59
	v_lshlrev_b32_e32 v54, 16, v60
	v_and_b32_e32 v55, 0xffff0000, v60
	v_pk_add_f32 v[48:49], v[48:49], v[54:55] neg_lo:[0,1] neg_hi:[0,1]
	v_lshlrev_b32_e32 v54, 16, v34
	v_pk_add_f32 v[22:23], v[22:23], v[48:49]
	v_lshlrev_b32_e32 v48, 16, v32
	v_and_b32_e32 v49, 0xffff0000, v32
	v_and_b32_e32 v55, 0xffff0000, v34
	v_pk_add_f32 v[48:49], v[48:49], v[54:55] neg_lo:[0,1] neg_hi:[0,1]
	v_lshlrev_b32_e32 v54, 16, v40
	v_pk_add_f32 v[48:49], v[20:21], v[48:49]
	v_lshlrev_b32_e32 v20, 16, v37
	v_and_b32_e32 v21, 0xffff0000, v37
	v_and_b32_e32 v55, 0xffff0000, v40
	v_and_b32_sdwa v42, v9, v203 dst_sel:DWORD dst_unused:UNUSED_PAD src0_sel:WORD_1 src1_sel:DWORD
	v_pk_add_f32 v[20:21], v[20:21], v[54:55] neg_lo:[0,1] neg_hi:[0,1]
	v_add3_u32 v9, v9, v42, s54
	v_pk_add_f32 v[20:21], v[48:49], v[20:21]
	v_and_b32_e32 v55, 0xffff0000, v6
	v_lshlrev_b32_e32 v54, 16, v6
	v_and_b32_e32 v9, 0xffff0000, v9
	v_pk_fma_f32 v[54:55], v[26:27], v[20:21], v[54:55] op_sel_hi:[0,1,1] neg_lo:[0,0,1] neg_hi:[0,0,1]
	v_and_b32_sdwa v45, v8, v203 dst_sel:DWORD dst_unused:UNUSED_PAD src0_sel:WORD_1 src1_sel:DWORD
	v_or_b32_sdwa v9, v9, v15 dst_sel:DWORD dst_unused:UNUSED_PAD src0_sel:DWORD src1_sel:WORD_1
	v_and_b32_sdwa v6, v55, v203 dst_sel:DWORD dst_unused:UNUSED_PAD src0_sel:WORD_1 src1_sel:DWORD
	v_and_b32_sdwa v15, v54, v203 dst_sel:DWORD dst_unused:UNUSED_PAD src0_sel:WORD_1 src1_sel:DWORD
	v_add3_u32 v8, v8, v45, s54
	v_add3_u32 v6, v55, v6, s54
	v_add3_u32 v15, v54, v15, s54
	v_lshlrev_b32_e32 v54, 16, v44
	v_and_b32_e32 v55, 0xffff0000, v44
	v_lshlrev_b32_e32 v44, 16, v46
	v_and_b32_e32 v45, 0xffff0000, v46
	v_pk_add_f32 v[44:45], v[54:55], v[44:45] neg_lo:[0,1] neg_hi:[0,1]
	v_lshrrev_b32_e32 v15, 16, v15
	v_pk_add_f32 v[20:21], v[20:21], v[44:45]
	v_and_b32_e32 v45, 0xffff0000, v10
	v_lshlrev_b32_e32 v44, 16, v10
	v_pk_fma_f32 v[44:45], v[28:29], v[20:21], v[44:45] op_sel_hi:[0,1,1] neg_lo:[0,0,1] neg_hi:[0,0,1]
	v_and_or_b32 v6, v6, s52, v15
	v_and_b32_sdwa v10, v45, v203 dst_sel:DWORD dst_unused:UNUSED_PAD src0_sel:WORD_1 src1_sel:DWORD
	v_and_b32_sdwa v15, v44, v203 dst_sel:DWORD dst_unused:UNUSED_PAD src0_sel:WORD_1 src1_sel:DWORD
	v_add3_u32 v10, v45, v10, s54
	v_add3_u32 v15, v44, v15, s54
	v_lshlrev_b32_e32 v44, 16, v50
	v_and_b32_e32 v45, 0xffff0000, v50
	v_lshlrev_b32_e32 v46, 16, v52
	v_and_b32_e32 v47, 0xffff0000, v52
	v_pk_add_f32 v[44:45], v[44:45], v[46:47] neg_lo:[0,1] neg_hi:[0,1]
	v_lshlrev_b32_e32 v46, 16, v30
	v_pk_add_f32 v[20:21], v[20:21], v[44:45]
	v_lshlrev_b32_e32 v44, 16, v27
	v_and_b32_e32 v45, 0xffff0000, v27
	v_and_b32_e32 v47, 0xffff0000, v30
	v_pk_add_f32 v[44:45], v[44:45], v[46:47] neg_lo:[0,1] neg_hi:[0,1]
	v_lshrrev_b32_e32 v15, 16, v15
	v_pk_add_f32 v[24:25], v[24:25], v[44:45]
	v_lshlrev_b32_e32 v45, 16, v3
	v_lshlrev_b32_e32 v44, 16, v2
	v_mov_b32_e32 v46, v48
	v_mov_b32_e32 v47, v24
	v_and_b32_e32 v3, 0xffff0000, v3
	v_and_b32_e32 v2, 0xffff0000, v2
	v_pk_fma_f32 v[44:45], v[14:15], v[46:47], v[44:45] op_sel_hi:[0,1,1] neg_lo:[0,0,1] neg_hi:[0,0,1]
	v_mov_b32_e32 v46, v49
	v_mov_b32_e32 v47, v25
	v_and_or_b32 v10, v10, s52, v15
	v_pk_fma_f32 v[2:3], v[14:15], v[46:47], v[2:3] op_sel_hi:[0,1,1] neg_lo:[0,0,1] neg_hi:[0,0,1]
	v_lshlrev_b32_e32 v14, 16, v31
	v_and_b32_e32 v15, 0xffff0000, v31
	v_lshlrev_b32_e32 v30, 16, v33
	v_and_b32_e32 v31, 0xffff0000, v33
	v_pk_add_f32 v[14:15], v[14:15], v[30:31] neg_lo:[0,1] neg_hi:[0,1]
	v_and_b32_e32 v8, 0xffff0000, v8
	v_pk_add_f32 v[14:15], v[24:25], v[14:15]
	v_and_b32_e32 v25, 0xffff0000, v7
	v_lshlrev_b32_e32 v24, 16, v7
	v_pk_fma_f32 v[24:25], v[26:27], v[14:15], v[24:25] op_sel_hi:[0,1,1] neg_lo:[0,0,1] neg_hi:[0,0,1]
	v_and_b32_sdwa v26, v24, v203 dst_sel:DWORD dst_unused:UNUSED_PAD src0_sel:WORD_1 src1_sel:DWORD
	v_and_b32_sdwa v7, v25, v203 dst_sel:DWORD dst_unused:UNUSED_PAD src0_sel:WORD_1 src1_sel:DWORD
	v_add3_u32 v24, v24, v26, s54
	v_add3_u32 v7, v25, v7, s54
	v_lshrrev_b32_e32 v24, 16, v24
	v_and_or_b32 v7, v7, s52, v24
	v_lshlrev_b32_e32 v24, 16, v35
	v_and_b32_e32 v25, 0xffff0000, v35
	v_lshlrev_b32_e32 v26, 16, v36
	v_and_b32_e32 v27, 0xffff0000, v36
	v_pk_add_f32 v[24:25], v[24:25], v[26:27] neg_lo:[0,1] neg_hi:[0,1]
	v_or_b32_sdwa v8, v8, v29 dst_sel:DWORD dst_unused:UNUSED_PAD src0_sel:DWORD src1_sel:WORD_1
	v_pk_add_f32 v[14:15], v[14:15], v[24:25]
	v_and_b32_e32 v25, 0xffff0000, v11
	v_lshlrev_b32_e32 v24, 16, v11
	v_pk_fma_f32 v[24:25], v[28:29], v[14:15], v[24:25] op_sel_hi:[0,1,1] neg_lo:[0,0,1] neg_hi:[0,0,1]
	v_bfe_u32 v28, v3, 16, 1
	v_bfe_u32 v29, v2, 16, 1
	v_bfe_u32 v30, v1, 16, 1
	v_bfe_u32 v31, v0, 16, 1
	v_and_b32_sdwa v26, v24, v203 dst_sel:DWORD dst_unused:UNUSED_PAD src0_sel:WORD_1 src1_sel:DWORD
	v_add3_u32 v0, v0, v31, s54
	v_add3_u32 v1, v1, v30, s54
	v_add3_u32 v2, v2, v29, s54
	v_add3_u32 v3, v3, v28, s54
	v_bfe_u32 v28, v66, 16, 1
	v_bfe_u32 v29, v67, 16, 1
	v_bfe_u32 v30, v44, 16, 1
	v_bfe_u32 v31, v45, 16, 1
	v_and_b32_sdwa v11, v25, v203 dst_sel:DWORD dst_unused:UNUSED_PAD src0_sel:WORD_1 src1_sel:DWORD
	v_add3_u32 v24, v24, v26, s54
	v_add3_u32 v31, v45, v31, s54
	v_add3_u32 v30, v44, v30, s54
	v_add3_u32 v29, v67, v29, s54
	v_add3_u32 v28, v66, v28, s54
	v_add3_u32 v11, v25, v11, s54
	v_lshrrev_b32_e32 v24, 16, v24
	v_lshrrev_b32_e32 v28, 16, v28
	v_lshrrev_b32_e32 v29, 16, v29
	v_lshrrev_b32_e32 v30, 16, v30
	v_lshrrev_b32_e32 v31, 16, v31
	v_and_or_b32 v11, v11, s52, v24
	v_lshlrev_b32_e32 v24, 16, v41
	v_and_b32_e32 v25, 0xffff0000, v41
	v_lshlrev_b32_e32 v26, 16, v43
	v_and_b32_e32 v27, 0xffff0000, v43
	v_and_or_b32 v3, v3, s52, v31
	v_and_or_b32 v2, v2, s52, v30
	v_and_or_b32 v1, v1, s52, v29
	v_and_or_b32 v0, v0, s52, v28
	global_store_dwordx4 v[12:13], v[0:3], off offset:1024
	global_store_dwordx4 v[12:13], v[4:7], off offset:2048
	global_store_dwordx4 v[12:13], v[8:11], off offset:3072
	v_pk_add_f32 v[0:1], v[24:25], v[26:27] neg_lo:[0,1] neg_hi:[0,1]
	v_pk_add_f32 v[18:19], v[64:65], v[18:19]
	v_pk_add_f32 v[24:25], v[14:15], v[0:1]
	s_cmp_lt_u32 s18, 12
	s_cbranch_scc1 .LBB0_613
	v_readlane_b32 s1, v253, 50
	s_add_i32 s8, s8, s88
	s_add_i32 s0, s0, s1
	s_cmpk_lt_i32 s8, 0x800
	s_cbranch_scc1 .LBB0_612
